# P7..P12 XCD-local: norm phases take the rows of their XCD's token tiles, the five grid barriers P7->P12 gather one XCD only (run-time guard: per-class XCC words + grid 256), on top of v26
# speedup vs baseline: 1.0058x; 1.0058x over previous
; #define LAS __attribute__((address_space(3)))
; __device__ __forceinline__ int lane_id() { int x; asm volatile("v_mbcnt_lo_u32_b32 %0, -1, 0\n\tv_mbcnt_hi_u32_b32 %0, -1, %0" : "=v"(x)); return x; }
; __device__ __forceinline__ unsigned xb_add(unsigned* p, unsigned v) { return __hip_atomic_fetch_add(p, v, __ATOMIC_RELAXED, __HIP_MEMORY_SCOPE_AGENT); }
; __device__ __forceinline__ unsigned xb_xcc_id() { return (unsigned)__builtin_amdgcn_s_getreg((3 << 11) | 20) & 0xFu; }
; __device__ __forceinline__ XcdBarrier xcd_barrier_post(unsigned* bar, volatile LAS unsigned* st, int wave) {
;     XcdBarrier b; b.bar = bar; b.x = xb_xcc_id(); b.st = st; b.w = wave;
;     if (wave == 0 && lane_id() == 0) (void)xb_add(&bar[XB_XCNT(b.x)], 1u);
;     return b;
; }
; __global__ void __launch_bounds__(NWAVES * 64, 2) hybrid_fwd(Args args) {
;     ...
;     XcdBarrier bar; bar.bar = (unsigned*)(C.ws + WS_CTL) + CW_BAR; bar.x = 0; bar.st = nullptr; bar.w = wave_s;
;     if (hi - lo > 1) bar = xcd_barrier_post((unsigned*)(C.ws + WS_CTL) + CW_BAR, MISC + 8, wave_s);
.LBB0_3:
	s_or_b64 exec, exec, s[4:5]
	v_readlane_b32 s0, v255, 0
	v_readlane_b32 s1, v255, 1
	s_add_u32 s0, s0, 0x4000
	v_writelane_b32 v255, s0, 4
	s_addc_u32 s0, s1, 0
	v_writelane_b32 v255, s0, 5
	s_sub_i32 s0, s89, s88
	s_mov_b32 s1, 0
	v_writelane_b32 v255, s1, 6
	s_cmp_gt_i32 s0, 1
	s_mov_b32 s0, 0
	v_writelane_b32 v255, s0, 7
	s_waitcnt lgkmcnt(0)
	s_barrier
	s_cbranch_scc0 .LBB0_9
	s_getreg_b32 s0, hwreg(HW_REG_XCC_ID, 0, 4)
	s_and_b32 s0, s0, 15
	v_writelane_b32 v255, s0, 6
	s_cmp_gt_u32 s90, 63
	s_cbranch_scc1 .LBB0_8
	v_mbcnt_lo_u32_b32 v0, -1, 0
	v_mbcnt_hi_u32_b32 v0, -1, v0
	s_nop 0
	v_cmp_eq_u32_e32 vcc, 0, v0
	s_and_saveexec_b64 s[4:5], vcc
	s_cbranch_execz .LBB0_7
	v_readlane_b32 s0, v255, 6
	s_lshl_b32 s0, s0, 8
	v_readlane_b32 s1, v255, 4
	s_add_u32 s0, s1, s0
	v_readlane_b32 s1, v255, 5
	s_addc_u32 s1, s1, 0
	v_mov_b32_e32 v2, 1
	v_mov_b64_e32 v[0:1], s[0:1]
	global_atomic_add v[0:1], v2, off offset:1024
	v_readlane_b32 s8, v255, 0
	v_readlane_b32 s9, v255, 1
	s_and_b32 s10, s2, 7
	s_lshl_b32 s10, s10, 2
	s_add_u32 s8, s8, s10
	s_addc_u32 s9, s9, 0
	s_add_u32 s8, s8, 0x3000
	s_addc_u32 s9, s9, 0
	v_readlane_b32 s10, v255, 6
	s_lshl_b32 s10, 1, s10
	v_mov_b32_e32 v3, s10
	v_mov_b64_e32 v[4:5], s[8:9]
	global_atomic_or v[4:5], v3, off

; __device__ __forceinline__ int lane_id() { int x; asm volatile("v_mbcnt_lo_u32_b32 %0, -1, 0\n\tv_mbcnt_hi_u32_b32 %0, -1, %0" : "=v"(x)); return x; }
; __device__ __forceinline__ unsigned xb_ld(unsigned* p)              { return __hip_atomic_load(p, __ATOMIC_RELAXED, __HIP_MEMORY_SCOPE_AGENT); }
; __device__ __forceinline__ unsigned xb_add(unsigned* p, unsigned v) { return __hip_atomic_fetch_add(p, v, __ATOMIC_RELAXED, __HIP_MEMORY_SCOPE_AGENT); }
; #define XB_SPIN(cond, bar) do { unsigned _sp = 0; while (cond) { __builtin_amdgcn_s_sleep(1); \
;     if ((++_sp & 255u) == 0u) { if (xb_ld(&(bar)[XB_TMO])) break; if (_sp > XB_SPIN_CAP) { atomicAdd(&(bar)[XB_TMO], 1u); break; } } } } while (0)
; __device__ __forceinline__ void xcd_barrier(const XcdBarrier& b) {
;     asm volatile("s_waitcnt vmcnt(0)" ::: "memory");
;     __syncthreads();
;     if (b.w == 0 && lane_id() == 0) {
;         unsigned* bar = b.bar;
;         __builtin_amdgcn_s_waitcnt(0);
;         unsigned nloc = b.st[0], nx = b.st[1];
;         if (nloc == 0u) { xcd_barrier_complete(bar, b.x, nloc, nx); b.st[0] = nloc; b.st[1] = nx; }
;         const unsigned old = xb_add(&bar[XB_XSUB(b.x)], 1u);
;         const unsigned gen = old / nloc;
;         if (old + 1u == (gen + 1u) * nloc) {
;             __builtin_amdgcn_fence(__ATOMIC_RELEASE, "agent");
;             asm volatile("s_waitcnt vmcnt(0)" ::: "memory");
;             const unsigned og = xb_add(&bar[XB_TOP], 1u);
;             const unsigned tg = og / nx;
;             if (og + 1u == (tg + 1u) * nx) xb_add(&bar[XB_TOPGEN], 1u);
;             else XB_SPIN(xb_ld(&bar[XB_TOPGEN]) == tg, bar);
.LBB0_1423:
	s_andn2_saveexec_b64 s[4:5], s[4:5]
	s_cbranch_execz .LBB0_1439
	v_readlane_b32 s4, v255, 0
	v_readlane_b32 s5, v255, 1
	s_add_u32 s40, s4, 0x3000
	s_addc_u32 s41, s5, 0
	v_mov_b64_e32 v[6:7], s[40:41]
	global_load_dwordx4 v[8:11], v[6:7], off sc1
	global_load_dwordx4 v[12:15], v[6:7], off offset:16 sc1
	s_waitcnt vmcnt(0)
	v_or3_b32 v6, v8, v9, v10
	v_or3_b32 v6, v6, v11, v12
	v_or3_b32 v6, v6, v13, v14
	v_or_b32_e32 v6, v6, v15
	v_add3_u32 v7, v8, v9, v10
	v_add3_u32 v7, v7, v11, v12
	v_add3_u32 v7, v7, v13, v14
	v_add_u32_e32 v7, v7, v15
	v_min3_u32 v8, v8, v9, v10
	v_min3_u32 v8, v8, v11, v12
	v_min3_u32 v8, v8, v13, v14
	v_min_u32_e32 v8, v8, v15
	s_nop 1
	v_readfirstlane_b32 s40, v6
	v_readfirstlane_b32 s41, v7
	v_readfirstlane_b32 s42, v8
	s_cmpk_eq_u32 s40, 0xff
	s_cselect_b32 s40, 1, 0
	s_cmpk_eq_u32 s41, 0xff
	s_cselect_b32 s41, 1, 0
	s_and_b32 s40, s40, s41
	s_cmp_lg_u32 s42, 0
	s_cselect_b32 s41, 1, 0
	s_and_b32 s40, s40, s41
	s_cmpk_eq_u32 s78, 0x100
	s_cselect_b32 s41, 1, 0
	s_and_b32 s40, s40, s41
	s_cmp_lg_u32 s40, 0
	s_cbranch_scc1 .Lxbloc_4
	buffer_wbl2 sc1
	v_mov_b32_e32 v1, s4
	v_add_co_u32_e32 v2, vcc, 0x7000, v1
	v_mov_b32_e32 v1, s5
	s_waitcnt vmcnt(0)
	s_nop 0
	v_addc_co_u32_e32 v3, vcc, 0, v1, vcc
	v_mov_b32_e32 v1, 1
	global_atomic_add v1, v[2:3], v1, off offset:1024 sc0
	v_cvt_f32_u32_e32 v2, v0
	v_sub_u32_e32 v3, 0, v0
	s_add_u32 s4, s4, 0x7500
	s_addc_u32 s5, s5, 0
	v_rcp_iflag_f32_e32 v2, v2
	s_mov_b64 s[8:9], -1
	v_mul_f32_e32 v2, 0x4f7ffffe, v2
	v_cvt_u32_f32_e32 v2, v2
	v_mul_lo_u32 v3, v3, v2
	v_mul_hi_u32 v3, v2, v3
	v_add_u32_e32 v2, v2, v3
	s_waitcnt vmcnt(0) lgkmcnt(0)
	v_mul_hi_u32 v2, v1, v2
	v_mul_lo_u32 v4, v2, v0
	v_add_u32_e32 v3, 1, v1
	v_sub_u32_e32 v1, v1, v4
	v_add_u32_e32 v5, 1, v2
	v_cmp_ge_u32_e32 vcc, v1, v0
	v_sub_u32_e32 v4, v1, v0
	s_nop 0
	v_cndmask_b32_e32 v2, v2, v5, vcc
	v_cndmask_b32_e32 v1, v1, v4, vcc
	v_add_u32_e32 v4, 1, v2
	v_cmp_ge_u32_e32 vcc, v1, v0
	s_nop 1
	v_cndmask_b32_e32 v2, v2, v4, vcc
	v_mad_u64_u32 v[0:1], s[6:7], v0, v2, v[0:1]
	v_cmp_ne_u32_e32 vcc, v3, v0
	v_mov_b64_e32 v[0:1], s[4:5]
	s_and_saveexec_b64 s[6:7], vcc
	s_cbranch_execz .LBB0_1436
	v_mov_b64_e32 v[0:1], s[4:5]
	global_load_dword v0, v[0:1], off sc1
	s_mov_b64 s[12:13], 0
	s_waitcnt vmcnt(0) lgkmcnt(0)
	v_cmp_eq_u32_e32 vcc, v0, v2
	s_and_saveexec_b64 s[10:11], vcc
	s_cbranch_execz .LBB0_1435
	v_readlane_b32 s8, v255, 0
	v_readlane_b32 s9, v255, 1
	s_add_u32 s8, s8, 0x4200
	s_addc_u32 s9, s9, 0
	s_mov_b32 s3, 1
	s_branch .LBB0_1428

; __device__ __forceinline__ unsigned xb_ld(unsigned* p)              { return __hip_atomic_load(p, __ATOMIC_RELAXED, __HIP_MEMORY_SCOPE_AGENT); }
; __device__ __forceinline__ unsigned xb_add(unsigned* p, unsigned v) { return __hip_atomic_fetch_add(p, v, __ATOMIC_RELAXED, __HIP_MEMORY_SCOPE_AGENT); }
; #define XB_SPIN(cond, bar) do { unsigned _sp = 0; while (cond) { __builtin_amdgcn_s_sleep(1); \
;     if ((++_sp & 255u) == 0u) { if (xb_ld(&(bar)[XB_TMO])) break; if (_sp > XB_SPIN_CAP) { atomicAdd(&(bar)[XB_TMO], 1u); break; } } } } while (0)
; __device__ __forceinline__ void xcd_barrier(const XcdBarrier& b) {
;     ...
;         const unsigned old = xb_add(&bar[XB_XSUB(b.x)], 1u);
;         const unsigned gen = old / nloc;
;         if (old + 1u == (gen + 1u) * nloc) {
;             __builtin_amdgcn_fence(__ATOMIC_RELEASE, "agent");
;             asm volatile("s_waitcnt vmcnt(0)" ::: "memory");
;             const unsigned og = xb_add(&bar[XB_TOP], 1u);
;             const unsigned tg = og / nx;
;             if (og + 1u == (tg + 1u) * nx) xb_add(&bar[XB_TOPGEN], 1u);
;             else XB_SPIN(xb_ld(&bar[XB_TOPGEN]) == tg, bar);
;             __builtin_amdgcn_fence(__ATOMIC_ACQUIRE, "agent");
;             xb_add(&bar[XB_XGEN(b.x)], 1u);
;             asm volatile("s_waitcnt vmcnt(0)" ::: "memory");
;         } else {
;             XB_SPIN(xb_ld(&bar[XB_XGEN(b.x)]) == gen, bar);
;             __builtin_amdgcn_fence(__ATOMIC_ACQUIRE, "agent");
;             asm volatile("s_waitcnt vmcnt(0)" ::: "memory");
;         }
.Lxbloc_4:
	v_mov_b32_e32 v0, s1
	v_add_co_u32_e32 v0, vcc, 0x2000, v0
	v_mov_b32_e32 v1, s0
	s_nop 0
	v_addc_co_u32_e32 v1, vcc, 0, v1, vcc
	v_mov_b32_e32 v2, 1
	s_waitcnt vmcnt(0) lgkmcnt(0)
	buffer_inv sc1
	global_atomic_add v[0:1], v2, off offset:1024
	s_waitcnt vmcnt(0)

; #define PHASE_BEGIN() do { LOAD_ARGS(); C.lane = launder_v(lane_id()); C.wave = wave_s; C.tid = C.wave * 64 + C.lane; C.gw = C.bid * NWAVES + C.wave; } while (0)
; __global__ void __launch_bounds__(NWAVES * 64, 2) hybrid_fwd(Args args) {
;     ...
;     if (IN(9)) { PHASE_BEGIN();
;         const float* MOD = WSP(float, WS_MOD);
; #pragma unroll 1
;         for (int r = 4 * C.gw; r < T; r += 4 * C.ngw)
;             rmsnorm_rows4<true, false, false>(WSP(float, WS_X1) + (size_t)r * 1024, 1024, C.in[10], MOD + 3072, MOD + 4096, WSP(bf16, WS_H2) + (size_t)r * 1024, 1024, C.lane);
.LBB0_1514:
	s_cmp_lt_i32 s88, 10
	s_cselect_b64 s[0:1], -1, 0
	s_and_b64 s[12:13], s[0:1], s[36:37]
	s_andn2_b64 vcc, exec, s[12:13]
	s_cbranch_vccnz .LBB0_1518
	s_mov_b64 s[4:5], s[92:93]
	v_readlane_b32 s0, v255, 8
	v_mbcnt_lo_u32_b32 v0, -1, 0
	v_mbcnt_hi_u32_b32 v0, -1, v0
	s_cmpk_gt_i32 s0, 0xfff
	v_readlane_b32 s1, v255, 9
	s_cbranch_scc1 .LBB0_1518
	v_mbcnt_lo_u32_b32 v1, -1, 0
	v_mbcnt_hi_u32_b32 v1, -1, v1
	v_and_b32_e32 v2, 64, v1
	v_add_u32_e32 v2, 64, v2
	v_xor_b32_e32 v3, 1, v1
	v_cmp_lt_i32_e32 vcc, v3, v2
	s_load_dwordx2 s[0:1], s[4:5], 0x50
	s_load_dwordx2 s[14:15], s[4:5], 0xc8
	v_cndmask_b32_e32 v3, v1, v3, vcc
	v_lshlrev_b32_e32 v93, 2, v3
	v_xor_b32_e32 v3, 2, v1
	v_cmp_lt_i32_e32 vcc, v3, v2
	v_readlane_b32 s4, v255, 8
	s_cmpk_lg_u32 s78, 0x100
	s_cbranch_scc1 .Lrows_p9_il
	s_bfe_u32 s16, s4, 0x30003
	s_lshl_b32 s16, s16, 11
	s_and_b32 s24, s4, 0xffffffc0
	s_add_i32 s16, s16, s24
	s_and_b32 s24, s4, 7
	s_lshl_b32 s24, s24, 3
	s_add_i32 s16, s16, s24
	s_add_i32 s24, s16, 8
	s_mov_b32 s18, 4
	s_branch .Lrows_p9_j
.Lrows_p9_il:
	s_lshl_b32 s16, s4, 2
	s_lshl_b32 s18, s78, 5
	s_movk_i32 s24, 0x4000
.Lrows_p9_j:
	v_cndmask_b32_e32 v3, v1, v3, vcc
	v_lshlrev_b32_e32 v95, 2, v3
	v_xor_b32_e32 v3, 4, v1
	v_cmp_lt_i32_e32 vcc, v3, v2
	s_ashr_i32 s17, s16, 31
	v_cndmask_b32_e32 v3, v1, v3, vcc
	v_lshlrev_b32_e32 v96, 2, v3
	v_xor_b32_e32 v3, 8, v1
	v_cmp_lt_i32_e32 vcc, v3, v2
	s_ashr_i32 s19, s18, 31
	s_lshl_b64 s[20:21], s[18:19], 11
	v_cndmask_b32_e32 v3, v1, v3, vcc
	v_lshlrev_b32_e32 v97, 2, v3
	v_xor_b32_e32 v3, 16, v1
	v_cmp_lt_i32_e32 vcc, v3, v2
	s_lshl_b64 s[22:23], s[18:19], 12
	v_mov_b32_e32 v100, 0x358637bd
	v_cndmask_b32_e32 v3, v1, v3, vcc
	v_lshlrev_b32_e32 v98, 2, v3
	v_xor_b32_e32 v3, 32, v1
	v_cmp_lt_i32_e32 vcc, v3, v2
	v_lshlrev_b32_e32 v2, 2, v0
	v_mov_b32_e32 v101, 0x260
	v_cndmask_b32_e32 v1, v1, v3, vcc
	v_ashrrev_i32_e32 v3, 31, v2
	v_lshlrev_b64 v[4:5], 2, v[2:3]
	s_waitcnt lgkmcnt(0)
	v_lshl_add_u64 v[72:73], s[0:1], 0, v[4:5]
	v_lshl_add_u64 v[4:5], s[14:15], 0, v[4:5]
	s_mov_b64 s[0:1], 0x2303000
	v_lshl_add_u64 v[74:75], v[4:5], 0, s[0:1]
	s_mov_b64 s[0:1], 0x2304000
	v_lshl_add_u64 v[76:77], v[4:5], 0, s[0:1]
	s_lshl_b64 s[0:1], s[16:17], 11
	v_lshlrev_b32_e32 v99, 2, v1
	v_ashrrev_i32_e32 v1, 31, v0
	v_lshl_add_u64 v[78:79], v[2:3], 1, s[0:1]
	s_lshl_b64 s[0:1], s[16:17], 12
	v_lshl_add_u64 v[80:81], v[0:1], 4, s[0:1]
	s_mov_b32 s0, 0xf800000
	s_mov_b32 s1, 0x2eacd000
	s_mov_b32 s3, 0x2eace000
	s_mov_b32 s17, 0x2eacf000
	v_readlane_b32 s5, v255, 9
.LBB0_1517:
	v_lshl_add_u64 v[12:13], s[14:15], 0, v[80:81]
	v_lshl_add_u64 v[0:1], s[14:15], 0, v[78:79]
	v_add_co_u32_e32 v2, vcc, 0x227cd000, v12
	v_add_co_u32_e64 v82, s[4:5], s1, v0
	s_nop 0
	v_addc_co_u32_e32 v3, vcc, 0, v13, vcc
	v_addc_co_u32_e64 v83, s[4:5], 0, v1, s[4:5]
	v_add_co_u32_e64 v84, s[4:5], s3, v0
	v_add_co_u32_e32 v4, vcc, 0x227ce000, v12
	s_nop 0
	v_addc_co_u32_e64 v85, s[4:5], 0, v1, s[4:5]
	v_addc_co_u32_e32 v5, vcc, 0, v13, vcc
	global_load_dwordx4 v[16:19], v[72:73], off
	global_load_dwordx4 v[102:105], v[76:77], off
	global_load_dwordx4 v[20:23], v[74:75], off
	v_add_co_u32_e64 v86, s[4:5], s17, v0
	global_load_dwordx4 v[68:71], v[2:3], off offset:2304
	global_load_dwordx4 v[60:63], v[2:3], off offset:3328
	v_add_co_u32_e32 v8, vcc, 0x227cf000, v12
	v_addc_co_u32_e64 v87, s[4:5], 0, v1, s[4:5]
	global_load_dwordx4 v[0:3], v[4:5], off offset:1280
	global_load_dwordx4 v[36:39], v[4:5], off offset:256
	global_load_dwordx4 v[64:67], v[4:5], off offset:2304
	global_load_dwordx4 v[52:55], v[4:5], off offset:3328
	v_addc_co_u32_e32 v9, vcc, 0, v13, vcc
	v_add_co_u32_e32 v14, vcc, 0x227d0000, v12
	global_load_dwordx4 v[4:7], v[8:9], off offset:1280
	global_load_dwordx4 v[32:35], v[8:9], off offset:256
	global_load_dwordx4 v[56:59], v[8:9], off offset:2304
	global_load_dwordx4 v[48:51], v[8:9], off offset:3328
	v_addc_co_u32_e32 v15, vcc, 0, v13, vcc
	v_add_co_u32_e32 v88, vcc, 0x227d1000, v12
	global_load_dwordx4 v[8:11], v[14:15], off offset:1280
	global_load_dwordx4 v[28:31], v[14:15], off offset:256
	global_load_dwordx4 v[44:47], v[14:15], off offset:2304
	global_load_dwordx4 v[40:43], v[14:15], off offset:3328
	v_addc_co_u32_e32 v89, vcc, 0, v13, vcc
	global_load_dwordx4 v[12:15], v[88:89], off offset:1280
	global_load_dwordx4 v[24:27], v[88:89], off offset:256
	s_add_i32 s16, s16, s18
	v_lshl_add_u64 v[78:79], v[78:79], 0, s[20:21]
	v_lshl_add_u64 v[80:81], v[80:81], 0, s[22:23]
	s_cmp_lt_i32 s16, s24
	s_waitcnt vmcnt(0) lgkmcnt(0)
; template <bool OUT_BF16, bool NT_IN, bool NT_OUT>
; __device__ __forceinline__ void rmsnorm_rows4(const float* src, size_t spitch, const float* g, const float* sh, const float* sc, void* dst, size_t dpitch, int lane) {
;     ...
; #pragma unroll
;         for (int j = 0; j < 4; ++j) v[q][j] = NT_IN ? __builtin_nontemporal_load(xr + 64 * j) : xr[64 * j]; }
; #pragma unroll
;     for (int q = 0; q < 4; ++q) { float a = 0.f;
; #pragma unroll
;         for (int j = 0; j < 4; ++j) a += (v[q][j][0] * v[q][j][0] + v[q][j][1] * v[q][j][1]) + (v[q][j][2] * v[q][j][2] + v[q][j][3] * v[q][j][3]);
;         ss[q] = a; }
; #pragma unroll
;     for (int q = 0; q < 4; ++q) ss[q] = 1.0f / sqrtf(wave_sum(ss[q]) * (1.0f / 1024.0f) + 1e-6f);
	v_pk_add_f32 v[88:89], v[104:105], 1.0 op_sel_hi:[1,0]
	v_pk_add_f32 v[90:91], v[102:103], 1.0 op_sel_hi:[1,0]
	v_pk_mul_f32 v[102:103], v[70:71], v[70:71]
	v_pk_mul_f32 v[104:105], v[68:69], v[68:69]
	v_pk_mul_f32 v[106:107], v[62:63], v[62:63]
	v_pk_mul_f32 v[108:109], v[60:61], v[60:61]
	v_pk_mov_b32 v[110:111], v[104:105], v[102:103] op_sel:[1,0]
	v_mov_b32_e32 v105, v103
	v_pk_mov_b32 v[102:103], v[108:109], v[106:107] op_sel:[1,0]
	v_mov_b32_e32 v109, v107
	v_mul_f32_e32 v92, v37, v37
	v_mul_f32_e32 v94, v39, v39
	v_pk_mul_f32 v[106:107], v[66:67], v[66:67]
	v_pk_mul_f32 v[112:113], v[64:65], v[64:65]
	v_pk_mul_f32 v[114:115], v[54:55], v[54:55]
	v_pk_mul_f32 v[116:117], v[52:53], v[52:53]
	v_mul_f32_e32 v126, v2, v2
	v_mul_f32_e32 v127, v3, v3
	v_pk_add_f32 v[104:105], v[110:111], v[104:105]
	v_pk_add_f32 v[102:103], v[102:103], v[108:109]
	v_pk_fma_f32 v[108:109], v[36:37], v[36:37], v[92:93] op_sel_hi:[1,1,0]
	v_pk_fma_f32 v[110:111], v[38:39], v[38:39], v[94:95] op_sel_hi:[1,1,0]
	v_pk_mov_b32 v[118:119], v[112:113], v[106:107] op_sel:[1,0]
	v_mov_b32_e32 v113, v107
	v_pk_mov_b32 v[106:107], v[116:117], v[114:115] op_sel:[1,0]
	v_mov_b32_e32 v117, v115
	v_pk_mul_f32 v[114:115], v[58:59], v[58:59]
	v_pk_mul_f32 v[120:121], v[56:57], v[56:57]
	v_pk_mul_f32 v[122:123], v[50:51], v[50:51]
	v_pk_mul_f32 v[124:125], v[48:49], v[48:49]
	v_mul_f32_e32 v134, v0, v0
	v_mul_f32_e32 v135, v1, v1
	v_mul_f32_e32 v92, v33, v33
	v_mul_f32_e32 v94, v35, v35
	v_pk_add_f32 v[104:105], v[104:105], v[104:105] op_sel:[0,1] op_sel_hi:[1,0]
	v_pk_add_f32 v[102:103], v[102:103], v[102:103] op_sel:[0,1] op_sel_hi:[1,0]
	v_mov_b32_e32 v109, v126
	v_mov_b32_e32 v111, v127
	v_pk_add_f32 v[112:113], v[118:119], v[112:113]
	v_pk_add_f32 v[106:107], v[106:107], v[116:117]
	v_pk_mov_b32 v[126:127], v[120:121], v[114:115] op_sel:[1,0]
	v_mov_b32_e32 v121, v115
	v_pk_mov_b32 v[114:115], v[124:125], v[122:123] op_sel:[1,0]
	v_mov_b32_e32 v125, v123
	v_mul_f32_e32 v136, v4, v4
	v_mul_f32_e32 v137, v5, v5
	v_mul_f32_e32 v138, v6, v6
	v_mul_f32_e32 v139, v7, v7
	v_pk_fma_f32 v[116:117], v[32:33], v[32:33], v[92:93] op_sel_hi:[1,1,0]
	v_pk_fma_f32 v[118:119], v[34:35], v[34:35], v[94:95] op_sel_hi:[1,1,0]
	v_mul_f32_e32 v92, v29, v29
	v_mul_f32_e32 v94, v31, v31
	v_pk_mul_f32 v[122:123], v[46:47], v[46:47]
	v_pk_mul_f32 v[128:129], v[44:45], v[44:45]
	v_pk_mul_f32 v[130:131], v[42:43], v[42:43]
	v_pk_mul_f32 v[132:133], v[40:41], v[40:41]
	v_mov_b32_e32 v105, v134
	v_mov_b32_e32 v103, v135
	v_pk_add_f32 v[108:109], v[108:109], v[110:111]
	v_pk_add_f32 v[110:111], v[112:113], v[112:113] op_sel:[0,1] op_sel_hi:[1,0]
	v_pk_add_f32 v[106:107], v[106:107], v[106:107] op_sel:[0,1] op_sel_hi:[1,0]
	v_pk_add_f32 v[112:113], v[126:127], v[120:121]
	v_pk_add_f32 v[114:115], v[114:115], v[124:125]
	v_mul_f32_e32 v140, v8, v8
	v_mul_f32_e32 v141, v9, v9
	v_mul_f32_e32 v142, v10, v10
	v_mul_f32_e32 v143, v11, v11
	v_mov_b32_e32 v117, v138
	v_mov_b32_e32 v119, v139
	v_pk_fma_f32 v[120:121], v[28:29], v[28:29], v[92:93] op_sel_hi:[1,1,0]
	v_pk_fma_f32 v[124:125], v[30:31], v[30:31], v[94:95] op_sel_hi:[1,1,0]
	v_pk_mov_b32 v[126:127], v[128:129], v[122:123] op_sel:[1,0]
	v_mov_b32_e32 v129, v123
	v_pk_mov_b32 v[122:123], v[132:133], v[130:131] op_sel:[1,0]
	v_mov_b32_e32 v133, v131
	v_pk_add_f32 v[102:103], v[104:105], v[102:103]
	v_mov_b32_e32 v111, v136
	v_mov_b32_e32 v107, v137
	v_pk_add_f32 v[112:113], v[112:113], v[112:113] op_sel:[0,1] op_sel_hi:[1,0]
	v_pk_add_f32 v[114:115], v[114:115], v[114:115] op_sel:[0,1] op_sel_hi:[1,0]
	v_mul_f32_e32 v92, v25, v25
	v_mul_f32_e32 v94, v27, v27
	v_pk_add_f32 v[104:105], v[116:117], v[118:119]
	v_mov_b32_e32 v121, v142
	v_mov_b32_e32 v125, v143
	v_pk_add_f32 v[116:117], v[126:127], v[128:129]
	v_pk_add_f32 v[118:119], v[122:123], v[132:133]
	v_pk_add_f32 v[102:103], v[102:103], v[108:109]
	v_pk_add_f32 v[106:107], v[110:111], v[106:107]
	v_mov_b32_e32 v113, v140
	v_mov_b32_e32 v115, v141
	v_mul_f32_e32 v130, v12, v12
	v_mul_f32_e32 v131, v13, v13
	v_mul_f32_e32 v134, v14, v14
	v_mul_f32_e32 v135, v15, v15
	v_pk_fma_f32 v[122:123], v[24:25], v[24:25], v[92:93] op_sel_hi:[1,1,0]
	v_pk_fma_f32 v[126:127], v[26:27], v[26:27], v[94:95] op_sel_hi:[1,1,0]
	v_pk_add_f32 v[108:109], v[120:121], v[124:125]
	v_pk_add_f32 v[110:111], v[116:117], v[116:117] op_sel:[0,1] op_sel_hi:[1,0]
	v_pk_add_f32 v[116:117], v[118:119], v[118:119] op_sel:[0,1] op_sel_hi:[1,0]
	v_add_f32_e32 v92, v102, v103
	v_pk_add_f32 v[102:103], v[106:107], v[104:105]
	v_pk_add_f32 v[104:105], v[112:113], v[114:115]
	v_mov_b32_e32 v123, v134
	v_mov_b32_e32 v127, v135
	v_mov_b32_e32 v111, v130
	v_mov_b32_e32 v117, v131
	v_add_f32_e32 v94, v102, v103
	v_pk_add_f32 v[102:103], v[104:105], v[108:109]
	ds_bpermute_b32 v108, v93, v92
	v_pk_add_f32 v[106:107], v[122:123], v[126:127]
	v_pk_add_f32 v[104:105], v[110:111], v[116:117]
	v_add_f32_e32 v109, v102, v103
	v_pk_add_f32 v[102:103], v[104:105], v[106:107]
	ds_bpermute_b32 v104, v93, v94
	v_add_f32_e32 v102, v102, v103
	ds_bpermute_b32 v103, v93, v109
	ds_bpermute_b32 v105, v93, v102
	s_waitcnt lgkmcnt(3)
	v_add_f32_e32 v92, v92, v108
	ds_bpermute_b32 v106, v95, v92
	s_waitcnt lgkmcnt(3)
	v_add_f32_e32 v94, v94, v104
	ds_bpermute_b32 v104, v95, v94
	s_waitcnt lgkmcnt(3)
	v_add_f32_e32 v103, v109, v103
	s_waitcnt lgkmcnt(2)
	v_add_f32_e32 v102, v102, v105
	ds_bpermute_b32 v107, v95, v103
	ds_bpermute_b32 v105, v95, v102
	s_waitcnt lgkmcnt(3)
	v_add_f32_e32 v92, v92, v106
	ds_bpermute_b32 v106, v96, v92
	s_waitcnt lgkmcnt(3)
	v_add_f32_e32 v94, v94, v104
	ds_bpermute_b32 v104, v96, v94
	s_waitcnt lgkmcnt(3)
; template <bool OUT_BF16, bool NT_IN, bool NT_OUT>
; __device__ __forceinline__ void rmsnorm_rows4(const float* src, size_t spitch, const float* g, const float* sh, const float* sc, void* dst, size_t dpitch, int lane) {
;     ...
;     for (int q = 0; q < 4; ++q) ss[q] = 1.0f / sqrtf(wave_sum(ss[q]) * (1.0f / 1024.0f) + 1e-6f);
; #pragma unroll
;     for (int j = 0; j < 4; ++j) {
;         const int k = 4 * lane + 256 * j;
;         const f4 gv = *(const f4*)(g + k); f4 scv = {1.f, 1.f, 1.f, 1.f}, shv = {0.f, 0.f, 0.f, 0.f};
;         if (sc) { scv = *(const f4*)(sc + k) + 1.0f; shv = *(const f4*)(sh + k); }
; #pragma unroll
;         for (int q = 0; q < 4; ++q) {
;             f4 y = v[q][j] * ss[q] * gv;
	v_add_f32_e32 v103, v103, v107
	s_waitcnt lgkmcnt(2)
	v_add_f32_e32 v102, v102, v105
	ds_bpermute_b32 v107, v96, v103
	ds_bpermute_b32 v105, v96, v102
	s_waitcnt lgkmcnt(3)
	v_add_f32_e32 v92, v92, v106
	ds_bpermute_b32 v106, v97, v92
	s_waitcnt lgkmcnt(3)
	v_add_f32_e32 v94, v94, v104
	ds_bpermute_b32 v104, v97, v94
	s_waitcnt lgkmcnt(3)
	v_add_f32_e32 v103, v103, v107
	s_waitcnt lgkmcnt(2)
	v_add_f32_e32 v102, v102, v105
	ds_bpermute_b32 v107, v97, v103
	ds_bpermute_b32 v105, v97, v102
	s_waitcnt lgkmcnt(3)
	v_add_f32_e32 v92, v92, v106
	ds_bpermute_b32 v106, v98, v92
	s_waitcnt lgkmcnt(3)
	v_add_f32_e32 v94, v94, v104
	ds_bpermute_b32 v104, v98, v94
	s_waitcnt lgkmcnt(3)
	v_add_f32_e32 v103, v103, v107
	s_waitcnt lgkmcnt(2)
	v_add_f32_e32 v102, v102, v105
	ds_bpermute_b32 v107, v98, v103
	ds_bpermute_b32 v105, v98, v102
	s_waitcnt lgkmcnt(3)
	v_add_f32_e32 v92, v92, v106
	ds_bpermute_b32 v106, v99, v92
	s_waitcnt lgkmcnt(3)
	v_add_f32_e32 v94, v94, v104
	ds_bpermute_b32 v104, v99, v94
	s_waitcnt lgkmcnt(3)
	v_add_f32_e32 v103, v103, v107
	s_waitcnt lgkmcnt(2)
	v_add_f32_e32 v102, v102, v105
	ds_bpermute_b32 v107, v99, v103
	ds_bpermute_b32 v105, v99, v102
	s_waitcnt lgkmcnt(3)
	v_add_f32_e32 v92, v92, v106
	v_fmamk_f32 v92, v92, 0x3a800000, v100
	s_waitcnt lgkmcnt(2)
	v_add_f32_e32 v94, v94, v104
	v_mul_f32_e32 v104, 0x4f800000, v92
	v_cmp_gt_f32_e32 vcc, s0, v92
	v_fmamk_f32 v94, v94, 0x3a800000, v100
	s_waitcnt lgkmcnt(1)
	v_add_f32_e32 v103, v103, v107
	v_cndmask_b32_e32 v92, v92, v104, vcc
	v_mul_f32_e32 v104, 0x4f800000, v94
	v_cmp_gt_f32_e64 s[4:5], s0, v94
	s_waitcnt lgkmcnt(0)
	v_add_f32_e32 v102, v102, v105
	v_sqrt_f32_e32 v105, v92
	v_fmamk_f32 v103, v103, 0x3a800000, v100
	v_cndmask_b32_e64 v94, v94, v104, s[4:5]
	v_mul_f32_e32 v104, 0x4f800000, v103
	v_cmp_gt_f32_e64 s[6:7], s0, v103
	v_fmamk_f32 v102, v102, 0x3a800000, v100
	v_sqrt_f32_e32 v106, v94
	v_cndmask_b32_e64 v103, v103, v104, s[6:7]
	v_mul_f32_e32 v104, 0x4f800000, v102
	v_cmp_gt_f32_e64 s[8:9], s0, v102
	v_sqrt_f32_e32 v107, v103
	v_add_u32_e32 v108, -1, v105
	v_cndmask_b32_e64 v102, v102, v104, s[8:9]
	v_sqrt_f32_e32 v104, v102
	v_add_u32_e32 v109, 1, v105
	v_fma_f32 v110, -v108, v105, v92
	v_fma_f32 v111, -v109, v105, v92
	v_add_u32_e32 v112, -1, v106
	v_cmp_ge_f32_e64 s[10:11], 0, v110
	v_add_u32_e32 v113, 1, v106
	v_fma_f32 v110, -v113, v106, v94
	v_cndmask_b32_e64 v105, v105, v108, s[10:11]
	v_fma_f32 v108, -v112, v106, v94
	v_cmp_lt_f32_e64 s[10:11], 0, v111
	v_add_u32_e32 v114, -1, v107
	v_add_u32_e32 v115, 1, v107
	v_cndmask_b32_e64 v105, v105, v109, s[10:11]
	v_cmp_ge_f32_e64 s[10:11], 0, v108
	v_fma_f32 v108, -v114, v107, v103
	v_fma_f32 v109, -v115, v107, v103
	v_cndmask_b32_e64 v106, v106, v112, s[10:11]
	v_cmp_lt_f32_e64 s[10:11], 0, v110
	v_add_u32_e32 v110, -1, v104
	v_add_u32_e32 v111, 1, v104
	v_mul_f32_e32 v112, 0x37800000, v105
	v_cndmask_b32_e64 v106, v106, v113, s[10:11]
	v_cmp_ge_f32_e64 s[10:11], 0, v108
	v_fma_f32 v108, -v110, v104, v102
	v_cndmask_b32_e32 v105, v105, v112, vcc
	v_cndmask_b32_e64 v107, v107, v114, s[10:11]
	v_cmp_lt_f32_e64 s[10:11], 0, v109
	v_fma_f32 v109, -v111, v104, v102
	v_cmp_ge_f32_e32 vcc, 0, v108
	v_mul_f32_e32 v112, 0x37800000, v106
	v_cndmask_b32_e64 v107, v107, v115, s[10:11]
	v_cndmask_b32_e32 v104, v104, v110, vcc
	v_cmp_lt_f32_e32 vcc, 0, v109
	v_cmp_class_f32_e64 s[10:11], v92, v101
	s_nop 0
	v_cndmask_b32_e32 v104, v104, v111, vcc
	v_cndmask_b32_e64 v92, v105, v92, s[10:11]
	v_cndmask_b32_e64 v105, v106, v112, s[4:5]
	v_cmp_class_f32_e64 s[4:5], v94, v101
	v_mul_f32_e32 v106, 0x37800000, v107
	v_div_scale_f32 v108, s[10:11], v92, v92, 1.0
	v_cndmask_b32_e64 v94, v105, v94, s[4:5]
	v_cndmask_b32_e64 v105, v107, v106, s[6:7]
	v_cmp_class_f32_e64 s[4:5], v103, v101
	v_mul_f32_e32 v106, 0x37800000, v104
	v_rcp_f32_e32 v107, v108
	v_div_scale_f32 v110, s[6:7], v94, v94, 1.0
	v_cndmask_b32_e64 v105, v105, v103, s[4:5]
	v_cndmask_b32_e64 v103, v104, v106, s[8:9]
	v_cmp_class_f32_e64 s[4:5], v102, v101
	v_rcp_f32_e32 v104, v110
	v_div_scale_f32 v106, s[8:9], v105, v105, 1.0
	v_cndmask_b32_e64 v113, v103, v102, s[4:5]
	v_rcp_f32_e32 v102, v106
	v_div_scale_f32 v103, s[4:5], v113, v113, 1.0
	v_rcp_f32_e32 v115, v103
	v_fma_f32 v116, -v108, v107, 1.0
	v_div_scale_f32 v109, vcc, 1.0, v92, 1.0
	v_fmac_f32_e32 v107, v116, v107
	v_fma_f32 v116, -v110, v104, 1.0
	v_div_scale_f32 v111, s[6:7], 1.0, v94, 1.0
	v_mul_f32_e32 v117, v109, v107
	v_fmac_f32_e32 v104, v116, v104
	v_fma_f32 v116, -v106, v102, 1.0
	v_div_scale_f32 v112, s[8:9], 1.0, v105, 1.0
	v_fma_f32 v118, -v108, v117, v109
	v_mul_f32_e32 v119, v111, v104
	v_fmac_f32_e32 v102, v116, v102
	v_fma_f32 v116, -v103, v115, 1.0
	v_div_scale_f32 v114, s[4:5], 1.0, v113, 1.0
	v_fmac_f32_e32 v117, v118, v107
	v_fma_f32 v118, -v110, v119, v111
	v_mul_f32_e32 v120, v112, v102
	v_fmac_f32_e32 v115, v116, v115
	v_fma_f32 v108, -v108, v117, v109
	v_fmac_f32_e32 v119, v118, v104
	v_fma_f32 v109, -v106, v120, v112
	v_mul_f32_e32 v116, v114, v115
	v_div_fmas_f32 v107, v108, v107, v117
	v_fma_f32 v108, -v110, v119, v111
	v_fmac_f32_e32 v120, v109, v102
	v_fma_f32 v109, -v103, v116, v114
	s_mov_b64 vcc, s[6:7]
	v_div_fmas_f32 v104, v108, v104, v119
	v_fma_f32 v106, -v106, v120, v112
	v_fmac_f32_e32 v116, v109, v115
	s_mov_b64 vcc, s[8:9]
	v_div_fixup_f32 v92, v107, v92, 1.0
	v_div_fixup_f32 v94, v104, v94, 1.0
	v_div_fmas_f32 v104, v106, v102, v120
	v_fma_f32 v106, -v103, v116, v114
	s_mov_b64 vcc, s[4:5]
	v_pk_mul_f32 v[102:103], v[60:61], v[92:93] op_sel_hi:[1,0]
	v_div_fmas_f32 v61, v106, v115, v116
	v_div_fixup_f32 v60, v104, v105, 1.0
	v_pk_mul_f32 v[104:105], v[52:53], v[94:95] op_sel_hi:[1,0]
; __device__ __forceinline__ unsigned cvtpk(float lo, float hi) { unsigned r; asm("v_cvt_pk_bf16_f32 %0, %1, %2" : "=v"(r) : "v"(lo), "v"(hi)); return r; }
; template <bool OUT_BF16, bool NT_IN, bool NT_OUT>
; __device__ __forceinline__ void rmsnorm_rows4(const float* src, size_t spitch, const float* g, const float* sh, const float* sc, void* dst, size_t dpitch, int lane) {
;     ...
;     for (int j = 0; j < 4; ++j) {
;         const int k = 4 * lane + 256 * j;
;         const f4 gv = *(const f4*)(g + k); f4 scv = {1.f, 1.f, 1.f, 1.f}, shv = {0.f, 0.f, 0.f, 0.f};
;         if (sc) { scv = *(const f4*)(sc + k) + 1.0f; shv = *(const f4*)(sh + k); }
; #pragma unroll
;         for (int q = 0; q < 4; ++q) {
;             f4 y = v[q][j] * ss[q] * gv;
;             if (sc) y = y * scv + shv;
;             if (OUT_BF16) { v2u w; w.x = cvtpk(y[0], y[1]); w.y = cvtpk(y[2], y[3]); *(v2u*)((bf16*)dst + (size_t)q * dpitch + k) = w; }
;             else { if (NT_OUT) __builtin_nontemporal_store(y, (f4*)((float*)dst + (size_t)q * dpitch + k)); else *(f4*)((float*)dst + (size_t)q * dpitch + k) = y; }
;         }
	v_div_fixup_f32 v52, v61, v113, 1.0
	v_pk_mul_f32 v[70:71], v[70:71], v[92:93] op_sel_hi:[1,0]
	v_pk_mul_f32 v[68:69], v[68:69], v[92:93] op_sel_hi:[1,0]
	v_pk_mul_f32 v[66:67], v[66:67], v[94:95] op_sel_hi:[1,0]
	v_pk_mul_f32 v[64:65], v[64:65], v[94:95] op_sel_hi:[1,0]
	v_pk_mul_f32 v[56:57], v[56:57], v[60:61] op_sel_hi:[1,0]
	v_pk_mul_f32 v[44:45], v[44:45], v[52:53] op_sel_hi:[1,0]
	v_pk_mul_f32 v[68:69], v[68:69], v[16:17]
	v_pk_mul_f32 v[70:71], v[70:71], v[18:19]
	v_pk_mul_f32 v[64:65], v[64:65], v[16:17]
	v_pk_mul_f32 v[66:67], v[66:67], v[18:19]
	v_pk_mul_f32 v[58:59], v[58:59], v[60:61] op_sel_hi:[1,0]
	v_pk_mul_f32 v[56:57], v[16:17], v[56:57]
	v_pk_mul_f32 v[46:47], v[46:47], v[52:53] op_sel_hi:[1,0]
	v_pk_mul_f32 v[16:17], v[16:17], v[44:45]
	v_pk_fma_f32 v[70:71], v[70:71], v[88:89], v[22:23]
	v_pk_fma_f32 v[68:69], v[68:69], v[90:91], v[20:21]
	v_pk_fma_f32 v[66:67], v[66:67], v[88:89], v[22:23]
	v_pk_fma_f32 v[64:65], v[64:65], v[90:91], v[20:21]
	v_pk_mul_f32 v[58:59], v[18:19], v[58:59]
	v_pk_mul_f32 v[106:107], v[40:41], v[52:53] op_sel_hi:[1,0]
	v_cvt_pk_bf16_f32 v40, v64, v65
	v_cvt_pk_bf16_f32 v41, v66, v67
	v_pk_mul_f32 v[18:19], v[18:19], v[46:47]
	v_pk_fma_f32 v[16:17], v[90:91], v[16:17], v[20:21]
	v_cvt_pk_bf16_f32 v68, v68, v69
	v_cvt_pk_bf16_f32 v69, v70, v71
	v_pk_mul_f32 v[70:71], v[42:43], v[52:53] op_sel_hi:[1,0]
	global_store_dwordx2 v[82:83], v[68:69], off offset:2304
	v_pk_fma_f32 v[42:43], v[88:89], v[58:59], v[22:23]
	v_pk_fma_f32 v[56:57], v[90:91], v[56:57], v[20:21]
	global_store_dwordx2 v[84:85], v[40:41], off offset:256
	v_cvt_pk_bf16_f32 v40, v56, v57
	v_cvt_pk_bf16_f32 v41, v42, v43
	v_pk_fma_f32 v[18:19], v[88:89], v[18:19], v[22:23]
	global_store_dwordx2 v[84:85], v[40:41], off offset:2304
	v_cvt_pk_bf16_f32 v16, v16, v17
	v_cvt_pk_bf16_f32 v17, v18, v19
	global_store_dwordx2 v[86:87], v[16:17], off offset:256
	global_load_dwordx4 v[16:19], v[76:77], off offset:1024
	s_nop 0
	global_load_dwordx4 v[20:23], v[72:73], off offset:1024
	global_load_dwordx4 v[40:43], v[74:75], off offset:1024
	v_pk_mul_f32 v[62:63], v[62:63], v[92:93] op_sel_hi:[1,0]
	v_pk_mul_f32 v[48:49], v[48:49], v[60:61] op_sel_hi:[1,0]
	v_pk_mul_f32 v[54:55], v[54:55], v[94:95] op_sel_hi:[1,0]
	v_pk_mul_f32 v[50:51], v[50:51], v[60:61] op_sel_hi:[1,0]
	v_pk_mul_f32 v[38:39], v[38:39], v[92:93] op_sel_hi:[1,0]
	v_pk_mul_f32 v[36:37], v[36:37], v[92:93] op_sel_hi:[1,0]
	v_pk_mul_f32 v[32:33], v[32:33], v[94:95] op_sel_hi:[1,0]
	v_pk_mul_f32 v[28:29], v[28:29], v[60:61] op_sel_hi:[1,0]
	v_pk_mul_f32 v[24:25], v[24:25], v[52:53] op_sel_hi:[1,0]
	v_pk_mul_f32 v[34:35], v[34:35], v[94:95] op_sel_hi:[1,0]
	v_pk_mul_f32 v[30:31], v[30:31], v[60:61] op_sel_hi:[1,0]
	v_pk_mul_f32 v[26:27], v[26:27], v[52:53] op_sel_hi:[1,0]
	v_pk_mul_f32 v[0:1], v[0:1], v[92:93] op_sel_hi:[1,0]
	v_pk_mul_f32 v[2:3], v[2:3], v[92:93] op_sel_hi:[1,0]
	v_pk_mul_f32 v[6:7], v[6:7], v[94:95] op_sel_hi:[1,0]
	v_pk_mul_f32 v[4:5], v[4:5], v[94:95] op_sel_hi:[1,0]
	v_pk_mul_f32 v[10:11], v[10:11], v[60:61] op_sel_hi:[1,0]
	v_pk_mul_f32 v[8:9], v[8:9], v[60:61] op_sel_hi:[1,0]
	v_pk_mul_f32 v[14:15], v[14:15], v[52:53] op_sel_hi:[1,0]
	v_pk_mul_f32 v[12:13], v[12:13], v[52:53] op_sel_hi:[1,0]
	s_waitcnt vmcnt(0) lgkmcnt(0)
; __device__ __forceinline__ unsigned cvtpk(float lo, float hi) { unsigned r; asm("v_cvt_pk_bf16_f32 %0, %1, %2" : "=v"(r) : "v"(lo), "v"(hi)); return r; }
; template <bool OUT_BF16, bool NT_IN, bool NT_OUT>
; __device__ __forceinline__ void rmsnorm_rows4(const float* src, size_t spitch, const float* g, const float* sh, const float* sc, void* dst, size_t dpitch, int lane) {
;     ...
;     for (int j = 0; j < 4; ++j) {
;         const int k = 4 * lane + 256 * j;
;         const f4 gv = *(const f4*)(g + k); f4 scv = {1.f, 1.f, 1.f, 1.f}, shv = {0.f, 0.f, 0.f, 0.f};
;         if (sc) { scv = *(const f4*)(sc + k) + 1.0f; shv = *(const f4*)(sh + k); }
; #pragma unroll
;         for (int q = 0; q < 4; ++q) {
;             f4 y = v[q][j] * ss[q] * gv;
;             if (sc) y = y * scv + shv;
;             if (OUT_BF16) { v2u w; w.x = cvtpk(y[0], y[1]); w.y = cvtpk(y[2], y[3]); *(v2u*)((bf16*)dst + (size_t)q * dpitch + k) = w; }
;             else { if (NT_OUT) __builtin_nontemporal_store(y, (f4*)((float*)dst + (size_t)q * dpitch + k)); else *(f4*)((float*)dst + (size_t)q * dpitch + k) = y; }
;         }
	v_pk_add_f32 v[18:19], v[18:19], 1.0 op_sel_hi:[1,0]
	v_pk_add_f32 v[16:17], v[16:17], 1.0 op_sel_hi:[1,0]
	v_pk_mul_f32 v[44:45], v[102:103], v[20:21]
	v_pk_mul_f32 v[46:47], v[62:63], v[22:23]
	v_pk_mul_f32 v[56:57], v[104:105], v[20:21]
	v_pk_mul_f32 v[48:49], v[48:49], v[20:21]
	v_pk_mul_f32 v[20:21], v[106:107], v[20:21]
	v_pk_mul_f32 v[54:55], v[54:55], v[22:23]
	v_pk_mul_f32 v[50:51], v[50:51], v[22:23]
	v_pk_mul_f32 v[22:23], v[70:71], v[22:23]
	v_pk_fma_f32 v[46:47], v[46:47], v[18:19], v[42:43]
	v_pk_fma_f32 v[44:45], v[44:45], v[16:17], v[40:41]
	v_pk_fma_f32 v[56:57], v[56:57], v[16:17], v[40:41]
	v_pk_fma_f32 v[48:49], v[48:49], v[16:17], v[40:41]
	v_pk_fma_f32 v[16:17], v[20:21], v[16:17], v[40:41]
	v_cvt_pk_bf16_f32 v20, v44, v45
	v_cvt_pk_bf16_f32 v21, v46, v47
	v_pk_fma_f32 v[54:55], v[54:55], v[18:19], v[42:43]
	v_pk_fma_f32 v[50:51], v[50:51], v[18:19], v[42:43]
	v_pk_fma_f32 v[18:19], v[22:23], v[18:19], v[42:43]
	v_cvt_pk_bf16_f32 v22, v56, v57
	v_cvt_pk_bf16_f32 v23, v54, v55
	v_cvt_pk_bf16_f32 v40, v48, v49
	v_cvt_pk_bf16_f32 v41, v50, v51
	v_cvt_pk_bf16_f32 v16, v16, v17
	s_nop 0
	v_cvt_pk_bf16_f32 v17, v18, v19
	global_store_dwordx2 v[82:83], v[20:21], off offset:2816
	global_store_dwordx2 v[84:85], v[22:23], off offset:768
	global_store_dwordx2 v[84:85], v[40:41], off offset:2816
	global_store_dwordx2 v[86:87], v[16:17], off offset:768
	global_load_dwordx4 v[16:19], v[76:77], off offset:2048
	s_nop 0
	global_load_dwordx4 v[20:23], v[72:73], off offset:2048
	global_load_dwordx4 v[40:43], v[74:75], off offset:2048
	s_waitcnt vmcnt(0) lgkmcnt(0)
	v_pk_add_f32 v[18:19], v[18:19], 1.0 op_sel_hi:[1,0]
	v_pk_add_f32 v[16:17], v[16:17], 1.0 op_sel_hi:[1,0]
	v_pk_mul_f32 v[36:37], v[36:37], v[20:21]
	v_pk_mul_f32 v[38:39], v[38:39], v[22:23]
	v_pk_mul_f32 v[32:33], v[32:33], v[20:21]
	v_pk_mul_f32 v[28:29], v[28:29], v[20:21]
	v_pk_mul_f32 v[20:21], v[24:25], v[20:21]
	v_pk_mul_f32 v[34:35], v[34:35], v[22:23]
	v_pk_mul_f32 v[30:31], v[30:31], v[22:23]
	v_pk_mul_f32 v[22:23], v[26:27], v[22:23]
	v_pk_fma_f32 v[24:25], v[38:39], v[18:19], v[42:43]
	v_pk_fma_f32 v[26:27], v[36:37], v[16:17], v[40:41]
	v_pk_fma_f32 v[32:33], v[32:33], v[16:17], v[40:41]
	v_pk_fma_f32 v[28:29], v[28:29], v[16:17], v[40:41]
	v_pk_fma_f32 v[16:17], v[20:21], v[16:17], v[40:41]
	v_cvt_pk_bf16_f32 v20, v26, v27
	v_cvt_pk_bf16_f32 v21, v24, v25
	v_pk_fma_f32 v[34:35], v[34:35], v[18:19], v[42:43]
	v_pk_fma_f32 v[30:31], v[30:31], v[18:19], v[42:43]
	v_pk_fma_f32 v[18:19], v[22:23], v[18:19], v[42:43]
	v_cvt_pk_bf16_f32 v22, v32, v33
	v_cvt_pk_bf16_f32 v23, v34, v35
	v_cvt_pk_bf16_f32 v24, v28, v29
	v_cvt_pk_bf16_f32 v25, v30, v31
	v_cvt_pk_bf16_f32 v16, v16, v17
	s_nop 0
	v_cvt_pk_bf16_f32 v17, v18, v19
	global_store_dwordx2 v[82:83], v[20:21], off offset:3328
	global_store_dwordx2 v[84:85], v[22:23], off offset:1280
	global_store_dwordx2 v[84:85], v[24:25], off offset:3328
	global_store_dwordx2 v[86:87], v[16:17], off offset:1280
	global_load_dwordx4 v[16:19], v[76:77], off offset:3072
	s_nop 0
	global_load_dwordx4 v[20:23], v[72:73], off offset:3072
	global_load_dwordx4 v[24:27], v[74:75], off offset:3072
	s_waitcnt vmcnt(0) lgkmcnt(0)
	v_pk_add_f32 v[16:17], v[16:17], 1.0 op_sel_hi:[1,0]
	v_pk_mul_f32 v[0:1], v[0:1], v[20:21]
	v_pk_add_f32 v[18:19], v[18:19], 1.0 op_sel_hi:[1,0]
	v_pk_mul_f32 v[2:3], v[2:3], v[22:23]
	v_pk_mul_f32 v[4:5], v[4:5], v[20:21]
	v_pk_mul_f32 v[6:7], v[6:7], v[22:23]
	v_pk_fma_f32 v[0:1], v[0:1], v[16:17], v[24:25]
	v_pk_mul_f32 v[8:9], v[8:9], v[20:21]
	v_pk_mul_f32 v[10:11], v[10:11], v[22:23]
	v_pk_mul_f32 v[12:13], v[12:13], v[20:21]
	v_pk_mul_f32 v[14:15], v[14:15], v[22:23]
	v_pk_fma_f32 v[2:3], v[2:3], v[18:19], v[26:27]
	v_pk_fma_f32 v[6:7], v[6:7], v[18:19], v[26:27]
	v_pk_fma_f32 v[4:5], v[4:5], v[16:17], v[24:25]
	v_cvt_pk_bf16_f32 v0, v0, v1
	v_cvt_pk_bf16_f32 v1, v2, v3
	v_pk_fma_f32 v[10:11], v[10:11], v[18:19], v[26:27]
	v_pk_fma_f32 v[8:9], v[8:9], v[16:17], v[24:25]
	v_pk_fma_f32 v[14:15], v[14:15], v[18:19], v[26:27]
	v_pk_fma_f32 v[12:13], v[12:13], v[16:17], v[24:25]
	v_cvt_pk_bf16_f32 v2, v4, v5
	v_cvt_pk_bf16_f32 v3, v6, v7
	v_cvt_pk_bf16_f32 v4, v8, v9
	v_cvt_pk_bf16_f32 v5, v10, v11
	v_cvt_pk_bf16_f32 v7, v14, v15
	s_nop 0
	v_cvt_pk_bf16_f32 v6, v12, v13
	global_store_dwordx2 v[82:83], v[0:1], off offset:3840
	global_store_dwordx2 v[84:85], v[2:3], off offset:1792
	global_store_dwordx2 v[84:85], v[4:5], off offset:3840
	global_store_dwordx2 v[86:87], v[6:7], off offset:1792
	s_cbranch_scc1 .LBB0_1517

; __device__ __forceinline__ int lane_id() { int x; asm volatile("v_mbcnt_lo_u32_b32 %0, -1, 0\n\tv_mbcnt_hi_u32_b32 %0, -1, %0" : "=v"(x)); return x; }
; __device__ __forceinline__ unsigned xb_ld(unsigned* p)              { return __hip_atomic_load(p, __ATOMIC_RELAXED, __HIP_MEMORY_SCOPE_AGENT); }
; __device__ __forceinline__ unsigned xb_add(unsigned* p, unsigned v) { return __hip_atomic_fetch_add(p, v, __ATOMIC_RELAXED, __HIP_MEMORY_SCOPE_AGENT); }
; #define XB_SPIN(cond, bar) do { unsigned _sp = 0; while (cond) { __builtin_amdgcn_s_sleep(1); \
;     if ((++_sp & 255u) == 0u) { if (xb_ld(&(bar)[XB_TMO])) break; if (_sp > XB_SPIN_CAP) { atomicAdd(&(bar)[XB_TMO], 1u); break; } } } } while (0)
; __device__ __forceinline__ void xcd_barrier(const XcdBarrier& b) {
;     asm volatile("s_waitcnt vmcnt(0)" ::: "memory");
;     __syncthreads();
;     if (b.w == 0 && lane_id() == 0) {
;         unsigned* bar = b.bar;
;         __builtin_amdgcn_s_waitcnt(0);
;         unsigned nloc = b.st[0], nx = b.st[1];
;         if (nloc == 0u) { xcd_barrier_complete(bar, b.x, nloc, nx); b.st[0] = nloc; b.st[1] = nx; }
;         const unsigned old = xb_add(&bar[XB_XSUB(b.x)], 1u);
;         const unsigned gen = old / nloc;
;         if (old + 1u == (gen + 1u) * nloc) {
;             __builtin_amdgcn_fence(__ATOMIC_RELEASE, "agent");
;             asm volatile("s_waitcnt vmcnt(0)" ::: "memory");
;             const unsigned og = xb_add(&bar[XB_TOP], 1u);
;             const unsigned tg = og / nx;
;             if (og + 1u == (tg + 1u) * nx) xb_add(&bar[XB_TOPGEN], 1u);
;             else XB_SPIN(xb_ld(&bar[XB_TOPGEN]) == tg, bar);
.LBB0_1694:
	s_andn2_saveexec_b64 s[2:3], s[2:3]
	s_cbranch_execz .LBB0_1710
	v_readlane_b32 s2, v255, 0
	v_readlane_b32 s3, v255, 1
	s_add_u32 s40, s2, 0x3000
	s_addc_u32 s41, s3, 0
	v_mov_b64_e32 v[6:7], s[40:41]
	global_load_dwordx4 v[8:11], v[6:7], off sc1
	global_load_dwordx4 v[12:15], v[6:7], off offset:16 sc1
	s_waitcnt vmcnt(0)
	v_or3_b32 v6, v8, v9, v10
	v_or3_b32 v6, v6, v11, v12
	v_or3_b32 v6, v6, v13, v14
	v_or_b32_e32 v6, v6, v15
	v_add3_u32 v7, v8, v9, v10
	v_add3_u32 v7, v7, v11, v12
	v_add3_u32 v7, v7, v13, v14
	v_add_u32_e32 v7, v7, v15
	v_min3_u32 v8, v8, v9, v10
	v_min3_u32 v8, v8, v11, v12
	v_min3_u32 v8, v8, v13, v14
	v_min_u32_e32 v8, v8, v15
	s_nop 1
	v_readfirstlane_b32 s40, v6
	v_readfirstlane_b32 s41, v7
	v_readfirstlane_b32 s42, v8
	s_cmpk_eq_u32 s40, 0xff
	s_cselect_b32 s40, 1, 0
	s_cmpk_eq_u32 s41, 0xff
	s_cselect_b32 s41, 1, 0
	s_and_b32 s40, s40, s41
	s_cmp_lg_u32 s42, 0
	s_cselect_b32 s41, 1, 0
	s_and_b32 s40, s40, s41
	s_cmpk_eq_u32 s78, 0x100
	s_cselect_b32 s41, 1, 0
	s_and_b32 s40, s40, s41
	s_cmp_lg_u32 s40, 0
	s_cbranch_scc1 .Lxbloc_8
	buffer_wbl2 sc1
	v_mov_b32_e32 v1, s2
	v_add_co_u32_e32 v2, vcc, 0x7000, v1
	v_mov_b32_e32 v1, s3
	s_waitcnt vmcnt(0)
	s_nop 0
	v_addc_co_u32_e32 v3, vcc, 0, v1, vcc
	v_mov_b32_e32 v1, 1
	global_atomic_add v1, v[2:3], v1, off offset:1024 sc0
	v_cvt_f32_u32_e32 v2, v0
	v_sub_u32_e32 v3, 0, v0
	s_add_u32 s2, s2, 0x7500
	s_addc_u32 s3, s3, 0
	v_rcp_iflag_f32_e32 v2, v2
	s_mov_b64 s[6:7], -1
	v_mul_f32_e32 v2, 0x4f7ffffe, v2
	v_cvt_u32_f32_e32 v2, v2
	v_mul_lo_u32 v3, v3, v2
	v_mul_hi_u32 v3, v2, v3
	v_add_u32_e32 v2, v2, v3
	s_waitcnt vmcnt(0) lgkmcnt(0)
	v_mul_hi_u32 v2, v1, v2
	v_mul_lo_u32 v4, v2, v0
	v_add_u32_e32 v3, 1, v1
	v_sub_u32_e32 v1, v1, v4
	v_add_u32_e32 v5, 1, v2
	v_cmp_ge_u32_e32 vcc, v1, v0
	v_sub_u32_e32 v4, v1, v0
	s_nop 0
	v_cndmask_b32_e32 v2, v2, v5, vcc
	v_cndmask_b32_e32 v1, v1, v4, vcc
	v_add_u32_e32 v4, 1, v2
	v_cmp_ge_u32_e32 vcc, v1, v0
	s_nop 1
	v_cndmask_b32_e32 v2, v2, v4, vcc
	v_mad_u64_u32 v[0:1], s[4:5], v0, v2, v[0:1]
	v_cmp_ne_u32_e32 vcc, v3, v0
	v_mov_b64_e32 v[0:1], s[2:3]
	s_and_saveexec_b64 s[4:5], vcc
	s_cbranch_execz .LBB0_1707
	v_mov_b64_e32 v[0:1], s[2:3]
	global_load_dword v0, v[0:1], off sc1
	s_mov_b64 s[10:11], 0
	s_waitcnt vmcnt(0) lgkmcnt(0)
	v_cmp_eq_u32_e32 vcc, v0, v2
	s_and_saveexec_b64 s[8:9], vcc
	s_cbranch_execz .LBB0_1706
	v_readlane_b32 s6, v255, 0
	v_readlane_b32 s7, v255, 1
	s_add_u32 s6, s6, 0x4200
	s_addc_u32 s7, s7, 0
	s_mov_b32 s22, 1
	s_branch .LBB0_1699

; #define PHASE_BEGIN() do { LOAD_ARGS(); C.lane = launder_v(lane_id()); C.wave = wave_s; C.tid = C.wave * 64 + C.lane; C.gw = C.bid * NWAVES + C.wave; } while (0)
; __global__ void __launch_bounds__(NWAVES * 64, 2) hybrid_fwd(Args args) {
;     ...
;     if (IN(12)) { PHASE_BEGIN();
; #pragma unroll 1
;         for (int r = 4 * C.gw; r < T; r += 4 * C.ngw)
;             rmsnorm_rows4<false, true, true>(WSP(float, WS_X2) + (size_t)r * 1024, 1024, C.in[11], nullptr, nullptr, C.out + O_Y + (size_t)r * 1024, 1024, C.lane);
.LBB0_1712:
	s_cmp_lt_i32 s88, 13
	s_cselect_b64 s[0:1], -1, 0
	s_and_b64 s[0:1], s[0:1], s[34:35]
	s_andn2_b64 vcc, exec, s[0:1]
	s_cbranch_vccnz .LBB0_1716
	v_readlane_b32 s0, v255, 8
	v_mbcnt_lo_u32_b32 v0, -1, 0
	v_mbcnt_hi_u32_b32 v0, -1, v0
	s_cmpk_gt_i32 s0, 0xfff
	v_readlane_b32 s1, v255, 9
	s_cbranch_scc1 .LBB0_1716
	v_mbcnt_lo_u32_b32 v1, -1, 0
	v_mbcnt_hi_u32_b32 v1, -1, v1
	v_and_b32_e32 v4, 64, v1
	v_add_u32_e32 v4, 64, v4
	v_xor_b32_e32 v5, 1, v1
	v_cmp_lt_i32_e32 vcc, v5, v4
	s_load_dwordx4 s[4:7], s[92:93], 0xc0
	s_load_dwordx2 s[0:1], s[92:93], 0x58
	v_cndmask_b32_e32 v5, v1, v5, vcc
	v_lshlrev_b32_e32 v82, 2, v5
	v_xor_b32_e32 v5, 2, v1
	v_cmp_lt_i32_e32 vcc, v5, v4
	v_readlane_b32 s2, v255, 8
	s_cmpk_lg_u32 s78, 0x100
	s_cbranch_scc1 .Lrows_p12_il
	s_bfe_u32 s8, s2, 0x30003
	s_lshl_b32 s8, s8, 11
	s_and_b32 s24, s2, 0xffffffc0
	s_add_i32 s8, s8, s24
	s_and_b32 s24, s2, 7
	s_lshl_b32 s24, s24, 3
	s_add_i32 s8, s8, s24
	s_add_i32 s24, s8, 8
	s_mov_b32 s10, 4
	s_branch .Lrows_p12_j
.Lrows_p12_il:
	s_lshl_b32 s8, s2, 2
	s_lshl_b32 s10, s78, 5
	s_movk_i32 s24, 0x4000
.Lrows_p12_j:
	v_cndmask_b32_e32 v5, v1, v5, vcc
	v_lshlrev_b32_e32 v83, 2, v5
	v_xor_b32_e32 v5, 4, v1
	v_cmp_lt_i32_e32 vcc, v5, v4
	s_waitcnt lgkmcnt(0)
	v_mov_b32_e32 v2, s6
	v_cndmask_b32_e32 v5, v1, v5, vcc
	v_lshlrev_b32_e32 v84, 2, v5
	v_xor_b32_e32 v5, 8, v1
	v_cmp_lt_i32_e32 vcc, v5, v4
	v_mov_b32_e32 v3, s7
	s_ashr_i32 s9, s8, 31
	v_cndmask_b32_e32 v5, v1, v5, vcc
	v_lshlrev_b32_e32 v85, 2, v5
	v_xor_b32_e32 v5, 16, v1
	v_cmp_lt_i32_e32 vcc, v5, v4
	s_ashr_i32 s11, s10, 31
	s_lshl_b64 s[12:13], s[8:9], 12
	v_cndmask_b32_e32 v5, v1, v5, vcc
	v_lshlrev_b32_e32 v86, 2, v5
	v_xor_b32_e32 v5, 32, v1
	v_cmp_lt_i32_e32 vcc, v5, v4
	v_lshlrev_b32_e32 v4, 2, v0
	s_lshl_b64 s[14:15], s[10:11], 12
	v_cndmask_b32_e32 v1, v1, v5, vcc
	v_ashrrev_i32_e32 v5, 31, v4
	v_lshlrev_b32_e32 v87, 2, v1
	v_ashrrev_i32_e32 v1, 31, v0
	v_lshlrev_b64 v[4:5], 2, v[4:5]
	v_lshl_add_u64 v[68:69], s[0:1], 0, v[4:5]
	v_lshl_add_u64 v[70:71], s[4:5], 0, v[4:5]
	v_lshl_add_u64 v[72:73], v[0:1], 4, v[2:3]
	v_mov_b32_e32 v88, 0x358637bd
	s_mov_b32 s9, 0xf800000
	v_mov_b32_e32 v89, 0x260
	s_movk_i32 s11, 0x1000
	s_movk_i32 s16, 0x2000
	s_movk_i32 s17, 0x3000
	v_readlane_b32 s3, v255, 9
.LBB0_1715:
	s_nop 0
	v_lshl_add_u64 v[12:13], v[72:73], 0, s[12:13]
	v_add_co_u32_e32 v0, vcc, 0x30b4d000, v12
	global_load_dwordx4 v[16:19], v[68:69], off
	s_nop 0
	v_addc_co_u32_e32 v1, vcc, 0, v13, vcc
	v_add_co_u32_e32 v4, vcc, 0x30b4e000, v12
	global_load_dwordx4 v[52:55], v[0:1], off offset:2304 nt
	global_load_dwordx4 v[48:51], v[0:1], off offset:3328 nt
	v_addc_co_u32_e32 v5, vcc, 0, v13, vcc
	v_add_co_u32_e32 v8, vcc, 0x30b4f000, v12
	global_load_dwordx4 v[0:3], v[4:5], off offset:1280 nt
	global_load_dwordx4 v[32:35], v[4:5], off offset:256 nt
	global_load_dwordx4 v[56:59], v[4:5], off offset:2304 nt
	global_load_dwordx4 v[44:47], v[4:5], off offset:3328 nt
	v_addc_co_u32_e32 v9, vcc, 0, v13, vcc
	v_add_co_u32_e32 v14, vcc, 0x30b50000, v12
	global_load_dwordx4 v[4:7], v[8:9], off offset:1280 nt
	global_load_dwordx4 v[28:31], v[8:9], off offset:256 nt
	global_load_dwordx4 v[60:63], v[8:9], off offset:2304 nt
	global_load_dwordx4 v[40:43], v[8:9], off offset:3328 nt
	v_addc_co_u32_e32 v15, vcc, 0, v13, vcc
	v_add_co_u32_e32 v90, vcc, 0x30b51000, v12
	global_load_dwordx4 v[8:11], v[14:15], off offset:1280 nt
	global_load_dwordx4 v[24:27], v[14:15], off offset:256 nt
	global_load_dwordx4 v[64:67], v[14:15], off offset:2304 nt
	global_load_dwordx4 v[36:39], v[14:15], off offset:3328 nt
	v_addc_co_u32_e32 v91, vcc, 0, v13, vcc
	global_load_dwordx4 v[12:15], v[90:91], off offset:1280 nt
	global_load_dwordx4 v[20:23], v[90:91], off offset:256 nt
	v_lshl_add_u64 v[74:75], v[70:71], 0, s[12:13]
	v_add_co_u32_e64 v76, s[0:1], s11, v74
	s_add_i32 s8, s8, s10
	s_nop 0
	v_addc_co_u32_e64 v77, s[0:1], 0, v75, s[0:1]
	v_add_co_u32_e64 v78, s[0:1], s16, v74
	v_lshl_add_u64 v[70:71], v[70:71], 0, s[14:15]
	s_nop 0
	v_addc_co_u32_e64 v79, s[0:1], 0, v75, s[0:1]
	v_add_co_u32_e64 v80, s[0:1], s17, v74
	v_lshl_add_u64 v[72:73], v[72:73], 0, s[14:15]
	s_nop 0
	v_addc_co_u32_e64 v81, s[0:1], 0, v75, s[0:1]
	s_cmp_lt_i32 s8, s24
	s_waitcnt vmcnt(0) lgkmcnt(0)
; template <bool OUT_BF16, bool NT_IN, bool NT_OUT>
; __device__ __forceinline__ void rmsnorm_rows4(const float* src, size_t spitch, const float* g, const float* sh, const float* sc, void* dst, size_t dpitch, int lane) {
;     ...
; #pragma unroll
;         for (int j = 0; j < 4; ++j) v[q][j] = NT_IN ? __builtin_nontemporal_load(xr + 64 * j) : xr[64 * j]; }
; #pragma unroll
;     for (int q = 0; q < 4; ++q) { float a = 0.f;
; #pragma unroll
;         for (int j = 0; j < 4; ++j) a += (v[q][j][0] * v[q][j][0] + v[q][j][1] * v[q][j][1]) + (v[q][j][2] * v[q][j][2] + v[q][j][3] * v[q][j][3]);
;         ss[q] = a; }
; #pragma unroll
;     for (int q = 0; q < 4; ++q) ss[q] = 1.0f / sqrtf(wave_sum(ss[q]) * (1.0f / 1024.0f) + 1e-6f);
	v_pk_mul_f32 v[90:91], v[54:55], v[54:55]
	v_pk_mul_f32 v[92:93], v[52:53], v[52:53]
	v_pk_mul_f32 v[94:95], v[50:51], v[50:51]
	v_pk_mul_f32 v[96:97], v[48:49], v[48:49]
	v_pk_mov_b32 v[98:99], v[92:93], v[90:91] op_sel:[1,0]
	v_mov_b32_e32 v93, v91
	v_pk_mov_b32 v[90:91], v[96:97], v[94:95] op_sel:[1,0]
	v_mov_b32_e32 v97, v95
	v_mul_f32_e32 v94, v33, v33
	v_mul_f32_e32 v100, v35, v35
	v_pk_mul_f32 v[102:103], v[58:59], v[58:59]
	v_pk_mul_f32 v[104:105], v[56:57], v[56:57]
	v_pk_mul_f32 v[106:107], v[46:47], v[46:47]
	v_pk_mul_f32 v[108:109], v[44:45], v[44:45]
	v_mul_f32_e32 v118, v2, v2
	v_mul_f32_e32 v119, v3, v3
	v_pk_add_f32 v[92:93], v[98:99], v[92:93]
	v_pk_add_f32 v[90:91], v[90:91], v[96:97]
	v_pk_fma_f32 v[94:95], v[32:33], v[32:33], v[94:95] op_sel_hi:[1,1,0]
	v_pk_fma_f32 v[96:97], v[34:35], v[34:35], v[100:101] op_sel_hi:[1,1,0]
	v_pk_mov_b32 v[98:99], v[104:105], v[102:103] op_sel:[1,0]
	v_mov_b32_e32 v105, v103
	v_pk_mov_b32 v[100:101], v[108:109], v[106:107] op_sel:[1,0]
	v_mov_b32_e32 v109, v107
	v_mul_f32_e32 v102, v29, v29
	v_mul_f32_e32 v106, v31, v31
	v_pk_mul_f32 v[110:111], v[62:63], v[62:63]
	v_pk_mul_f32 v[112:113], v[60:61], v[60:61]
	v_pk_mul_f32 v[114:115], v[42:43], v[42:43]
	v_pk_mul_f32 v[116:117], v[40:41], v[40:41]
	v_mul_f32_e32 v126, v0, v0
	v_mul_f32_e32 v127, v1, v1
	v_mul_f32_e32 v130, v6, v6
	v_mul_f32_e32 v131, v7, v7
	v_pk_add_f32 v[92:93], v[92:93], v[92:93] op_sel:[0,1] op_sel_hi:[1,0]
	v_pk_add_f32 v[90:91], v[90:91], v[90:91] op_sel:[0,1] op_sel_hi:[1,0]
	v_mov_b32_e32 v95, v118
	v_mov_b32_e32 v97, v119
	v_pk_add_f32 v[98:99], v[98:99], v[104:105]
	v_pk_add_f32 v[100:101], v[100:101], v[108:109]
	v_pk_fma_f32 v[102:103], v[28:29], v[28:29], v[102:103] op_sel_hi:[1,1,0]
	v_pk_fma_f32 v[104:105], v[30:31], v[30:31], v[106:107] op_sel_hi:[1,1,0]
	v_pk_mov_b32 v[106:107], v[112:113], v[110:111] op_sel:[1,0]
	v_mov_b32_e32 v113, v111
	v_pk_mov_b32 v[108:109], v[116:117], v[114:115] op_sel:[1,0]
	v_mov_b32_e32 v117, v115
	v_mul_f32_e32 v128, v4, v4
	v_mul_f32_e32 v129, v5, v5
	v_mul_f32_e32 v110, v25, v25
	v_mul_f32_e32 v114, v27, v27
	v_pk_mul_f32 v[118:119], v[66:67], v[66:67]
	v_pk_mul_f32 v[120:121], v[64:65], v[64:65]
	v_pk_mul_f32 v[122:123], v[38:39], v[38:39]
	v_pk_mul_f32 v[124:125], v[36:37], v[36:37]
	v_mov_b32_e32 v93, v126
	v_mov_b32_e32 v91, v127
	v_pk_add_f32 v[94:95], v[94:95], v[96:97]
	v_pk_add_f32 v[96:97], v[98:99], v[98:99] op_sel:[0,1] op_sel_hi:[1,0]
	v_pk_add_f32 v[98:99], v[100:101], v[100:101] op_sel:[0,1] op_sel_hi:[1,0]
	v_mov_b32_e32 v103, v130
	v_mov_b32_e32 v105, v131
	v_pk_add_f32 v[100:101], v[106:107], v[112:113]
	v_pk_add_f32 v[106:107], v[108:109], v[116:117]
	v_mul_f32_e32 v132, v8, v8
	v_mul_f32_e32 v133, v9, v9
	v_mul_f32_e32 v134, v10, v10
	v_mul_f32_e32 v135, v11, v11
	v_pk_fma_f32 v[108:109], v[24:25], v[24:25], v[110:111] op_sel_hi:[1,1,0]
	v_pk_fma_f32 v[110:111], v[26:27], v[26:27], v[114:115] op_sel_hi:[1,1,0]
	v_pk_mov_b32 v[112:113], v[120:121], v[118:119] op_sel:[1,0]
	v_mov_b32_e32 v121, v119
	v_pk_mov_b32 v[114:115], v[124:125], v[122:123] op_sel:[1,0]
	v_mov_b32_e32 v125, v123
	v_pk_add_f32 v[90:91], v[92:93], v[90:91]
	v_mov_b32_e32 v97, v128
	v_mov_b32_e32 v99, v129
	v_pk_add_f32 v[92:93], v[102:103], v[104:105]
	v_pk_add_f32 v[100:101], v[100:101], v[100:101] op_sel:[0,1] op_sel_hi:[1,0]
	v_pk_add_f32 v[102:103], v[106:107], v[106:107] op_sel:[0,1] op_sel_hi:[1,0]
	v_mul_f32_e32 v117, v12, v12
	v_mul_f32_e32 v119, v13, v13
	v_mul_f32_e32 v116, v21, v21
	v_mul_f32_e32 v118, v23, v23
	v_mov_b32_e32 v109, v134
	v_mov_b32_e32 v111, v135
	v_pk_add_f32 v[104:105], v[112:113], v[120:121]
	v_pk_add_f32 v[106:107], v[114:115], v[124:125]
	v_pk_add_f32 v[90:91], v[90:91], v[94:95]
	v_pk_add_f32 v[94:95], v[96:97], v[98:99]
	v_mov_b32_e32 v101, v132
	v_mov_b32_e32 v103, v133
	v_mul_f32_e32 v122, v14, v14
	v_mul_f32_e32 v123, v15, v15
	v_pk_fma_f32 v[112:113], v[20:21], v[20:21], v[116:117] op_sel_hi:[1,1,0]
	v_pk_fma_f32 v[114:115], v[22:23], v[22:23], v[118:119] op_sel_hi:[1,1,0]
	v_pk_add_f32 v[96:97], v[108:109], v[110:111]
	v_pk_add_f32 v[98:99], v[104:105], v[104:105] op_sel:[0,1] op_sel_hi:[1,0]
	v_pk_add_f32 v[104:105], v[106:107], v[106:107] op_sel:[0,1] op_sel_hi:[1,0]
	v_add_f32_e32 v106, v90, v91
	v_pk_add_f32 v[90:91], v[94:95], v[92:93]
	v_pk_add_f32 v[92:93], v[100:101], v[102:103]
	v_mov_b32_e32 v113, v122
	v_mov_b32_e32 v115, v123
	v_mov_b32_e32 v99, v117
	v_mov_b32_e32 v105, v119
	v_add_f32_e32 v100, v90, v91
	v_pk_add_f32 v[90:91], v[92:93], v[96:97]
	ds_bpermute_b32 v96, v82, v106
	v_pk_add_f32 v[94:95], v[112:113], v[114:115]
	v_pk_add_f32 v[92:93], v[98:99], v[104:105]
	v_add_f32_e32 v97, v90, v91
	v_pk_add_f32 v[90:91], v[92:93], v[94:95]
	ds_bpermute_b32 v92, v82, v100
	v_add_f32_e32 v90, v90, v91
	ds_bpermute_b32 v91, v82, v97
	ds_bpermute_b32 v93, v82, v90
	s_waitcnt lgkmcnt(3)
	v_add_f32_e32 v94, v106, v96
	ds_bpermute_b32 v95, v83, v94
	s_waitcnt lgkmcnt(3)
	v_add_f32_e32 v92, v100, v92
	ds_bpermute_b32 v96, v83, v92
	s_waitcnt lgkmcnt(3)
	v_add_f32_e32 v91, v97, v91
	s_waitcnt lgkmcnt(2)
	v_add_f32_e32 v90, v90, v93
	ds_bpermute_b32 v97, v83, v91
	ds_bpermute_b32 v93, v83, v90
	s_waitcnt lgkmcnt(3)
	v_add_f32_e32 v94, v94, v95
	ds_bpermute_b32 v95, v84, v94
	s_waitcnt lgkmcnt(3)
	v_add_f32_e32 v92, v92, v96
	ds_bpermute_b32 v96, v84, v92
	s_waitcnt lgkmcnt(3)
	v_add_f32_e32 v91, v91, v97
	s_waitcnt lgkmcnt(2)
	v_add_f32_e32 v90, v90, v93
	ds_bpermute_b32 v97, v84, v91
	ds_bpermute_b32 v93, v84, v90
	s_waitcnt lgkmcnt(3)
	v_add_f32_e32 v94, v94, v95
	ds_bpermute_b32 v95, v85, v94
	s_waitcnt lgkmcnt(3)
; template <bool OUT_BF16, bool NT_IN, bool NT_OUT>
; __device__ __forceinline__ void rmsnorm_rows4(const float* src, size_t spitch, const float* g, const float* sh, const float* sc, void* dst, size_t dpitch, int lane) {
;     ...
;     for (int q = 0; q < 4; ++q) ss[q] = 1.0f / sqrtf(wave_sum(ss[q]) * (1.0f / 1024.0f) + 1e-6f);
; #pragma unroll
;     for (int j = 0; j < 4; ++j) {
;         const int k = 4 * lane + 256 * j;
;         const f4 gv = *(const f4*)(g + k); f4 scv = {1.f, 1.f, 1.f, 1.f}, shv = {0.f, 0.f, 0.f, 0.f};
;         if (sc) { scv = *(const f4*)(sc + k) + 1.0f; shv = *(const f4*)(sh + k); }
; #pragma unroll
;         for (int q = 0; q < 4; ++q) {
;             f4 y = v[q][j] * ss[q] * gv;
	v_add_f32_e32 v92, v92, v96
	ds_bpermute_b32 v96, v85, v92
	s_waitcnt lgkmcnt(3)
	v_add_f32_e32 v91, v91, v97
	s_waitcnt lgkmcnt(2)
	v_add_f32_e32 v90, v90, v93
	ds_bpermute_b32 v97, v85, v91
	ds_bpermute_b32 v93, v85, v90
	s_waitcnt lgkmcnt(3)
	v_add_f32_e32 v94, v94, v95
	ds_bpermute_b32 v95, v86, v94
	s_waitcnt lgkmcnt(3)
	v_add_f32_e32 v92, v92, v96
	ds_bpermute_b32 v96, v86, v92
	s_waitcnt lgkmcnt(3)
	v_add_f32_e32 v91, v91, v97
	s_waitcnt lgkmcnt(2)
	v_add_f32_e32 v90, v90, v93
	ds_bpermute_b32 v97, v86, v91
	ds_bpermute_b32 v93, v86, v90
	s_waitcnt lgkmcnt(3)
	v_add_f32_e32 v94, v94, v95
	ds_bpermute_b32 v95, v87, v94
	s_waitcnt lgkmcnt(3)
	v_add_f32_e32 v92, v92, v96
	ds_bpermute_b32 v96, v87, v92
	s_waitcnt lgkmcnt(3)
	v_add_f32_e32 v91, v91, v97
	s_waitcnt lgkmcnt(2)
	v_add_f32_e32 v90, v90, v93
	ds_bpermute_b32 v97, v87, v91
	ds_bpermute_b32 v93, v87, v90
	s_waitcnt lgkmcnt(3)
	v_add_f32_e32 v94, v94, v95
	v_fmamk_f32 v94, v94, 0x3a800000, v88
	s_waitcnt lgkmcnt(2)
	v_add_f32_e32 v92, v92, v96
	v_mul_f32_e32 v95, 0x4f800000, v94
	v_cmp_gt_f32_e32 vcc, s9, v94
	v_fmamk_f32 v92, v92, 0x3a800000, v88
	s_waitcnt lgkmcnt(1)
	v_add_f32_e32 v91, v91, v97
	v_cndmask_b32_e32 v94, v94, v95, vcc
	v_mul_f32_e32 v95, 0x4f800000, v92
	v_cmp_gt_f32_e64 s[0:1], s9, v92
	s_waitcnt lgkmcnt(0)
	v_add_f32_e32 v90, v90, v93
	v_sqrt_f32_e32 v93, v94
	v_fmamk_f32 v91, v91, 0x3a800000, v88
	v_cndmask_b32_e64 v92, v92, v95, s[0:1]
	v_mul_f32_e32 v95, 0x4f800000, v91
	v_cmp_gt_f32_e64 s[2:3], s9, v91
	v_fmamk_f32 v90, v90, 0x3a800000, v88
	v_sqrt_f32_e32 v96, v92
	v_cndmask_b32_e64 v91, v91, v95, s[2:3]
	v_mul_f32_e32 v95, 0x4f800000, v90
	v_cmp_gt_f32_e64 s[4:5], s9, v90
	v_sqrt_f32_e32 v97, v91
	v_add_u32_e32 v98, -1, v93
	v_cndmask_b32_e64 v90, v90, v95, s[4:5]
	v_sqrt_f32_e32 v95, v90
	v_add_u32_e32 v99, 1, v93
	v_fma_f32 v100, -v98, v93, v94
	v_fma_f32 v101, -v99, v93, v94
	v_add_u32_e32 v102, -1, v96
	v_cmp_ge_f32_e64 s[6:7], 0, v100
	v_add_u32_e32 v103, 1, v96
	v_fma_f32 v100, -v103, v96, v92
	v_cndmask_b32_e64 v93, v93, v98, s[6:7]
	v_fma_f32 v98, -v102, v96, v92
	v_cmp_lt_f32_e64 s[6:7], 0, v101
	v_add_u32_e32 v104, -1, v97
	v_add_u32_e32 v105, 1, v97
	v_cndmask_b32_e64 v93, v93, v99, s[6:7]
	v_cmp_ge_f32_e64 s[6:7], 0, v98
	v_fma_f32 v98, -v104, v97, v91
	v_fma_f32 v99, -v105, v97, v91
	v_cndmask_b32_e64 v96, v96, v102, s[6:7]
	v_cmp_lt_f32_e64 s[6:7], 0, v100
	v_add_u32_e32 v100, -1, v95
	v_add_u32_e32 v101, 1, v95
	v_mul_f32_e32 v102, 0x37800000, v93
	v_cndmask_b32_e64 v96, v96, v103, s[6:7]
	v_cmp_ge_f32_e64 s[6:7], 0, v98
	v_fma_f32 v98, -v100, v95, v90
	v_cndmask_b32_e32 v93, v93, v102, vcc
	v_cndmask_b32_e64 v97, v97, v104, s[6:7]
	v_cmp_lt_f32_e64 s[6:7], 0, v99
	v_fma_f32 v99, -v101, v95, v90
	v_cmp_ge_f32_e32 vcc, 0, v98
	v_mul_f32_e32 v102, 0x37800000, v96
	v_cndmask_b32_e64 v97, v97, v105, s[6:7]
	v_cndmask_b32_e32 v95, v95, v100, vcc
	v_cmp_lt_f32_e32 vcc, 0, v99
	v_cmp_class_f32_e64 s[6:7], v94, v89
	s_nop 0
	v_cndmask_b32_e32 v95, v95, v101, vcc
	v_cndmask_b32_e64 v93, v93, v94, s[6:7]
	v_cndmask_b32_e64 v94, v96, v102, s[0:1]
	v_cmp_class_f32_e64 s[0:1], v92, v89
	v_mul_f32_e32 v96, 0x37800000, v97
	v_div_scale_f32 v98, s[6:7], v93, v93, 1.0
	v_cndmask_b32_e64 v92, v94, v92, s[0:1]
	v_cndmask_b32_e64 v94, v97, v96, s[2:3]
	v_cmp_class_f32_e64 s[0:1], v91, v89
	v_mul_f32_e32 v96, 0x37800000, v95
	v_rcp_f32_e32 v97, v98
	v_div_scale_f32 v100, s[2:3], v92, v92, 1.0
	v_cndmask_b32_e64 v91, v94, v91, s[0:1]
	v_cndmask_b32_e64 v94, v95, v96, s[4:5]
	v_cmp_class_f32_e64 s[0:1], v90, v89
	v_rcp_f32_e32 v95, v100
	v_div_scale_f32 v96, s[4:5], v91, v91, 1.0
	v_cndmask_b32_e64 v103, v94, v90, s[0:1]
	v_rcp_f32_e32 v94, v96
	v_div_scale_f32 v104, s[0:1], v103, v103, 1.0
	v_rcp_f32_e32 v106, v104
	v_fma_f32 v90, -v98, v97, 1.0
	v_div_scale_f32 v99, vcc, 1.0, v93, 1.0
	v_fmac_f32_e32 v97, v90, v97
	v_fma_f32 v90, -v100, v95, 1.0
	v_div_scale_f32 v101, s[2:3], 1.0, v92, 1.0
	v_mul_f32_e32 v107, v99, v97
	v_fmac_f32_e32 v95, v90, v95
	v_fma_f32 v90, -v96, v94, 1.0
	v_div_scale_f32 v102, s[4:5], 1.0, v91, 1.0
	v_fma_f32 v108, -v98, v107, v99
	v_mul_f32_e32 v109, v101, v95
	v_fmac_f32_e32 v94, v90, v94
	v_fma_f32 v90, -v104, v106, 1.0
	v_div_scale_f32 v105, s[0:1], 1.0, v103, 1.0
	v_fmac_f32_e32 v107, v108, v97
	v_fma_f32 v108, -v100, v109, v101
	v_mul_f32_e32 v110, v102, v94
	v_fmac_f32_e32 v106, v90, v106
	v_fma_f32 v90, -v98, v107, v99
	v_fmac_f32_e32 v109, v108, v95
	v_fma_f32 v98, -v96, v110, v102
	v_mul_f32_e32 v99, v105, v106
	v_div_fmas_f32 v90, v90, v97, v107
	v_fma_f32 v97, -v100, v109, v101
	v_fmac_f32_e32 v110, v98, v94
	v_fma_f32 v98, -v104, v99, v105
	s_mov_b64 vcc, s[2:3]
	v_div_fixup_f32 v90, v90, v93, 1.0
	v_div_fmas_f32 v93, v97, v95, v109
; __device__ __forceinline__ unsigned cvtpk(float lo, float hi) { unsigned r; asm("v_cvt_pk_bf16_f32 %0, %1, %2" : "=v"(r) : "v"(lo), "v"(hi)); return r; }
; template <bool OUT_BF16, bool NT_IN, bool NT_OUT>
; __device__ __forceinline__ void rmsnorm_rows4(const float* src, size_t spitch, const float* g, const float* sh, const float* sc, void* dst, size_t dpitch, int lane) {
;     ...
;     for (int j = 0; j < 4; ++j) {
;         const int k = 4 * lane + 256 * j;
;         const f4 gv = *(const f4*)(g + k); f4 scv = {1.f, 1.f, 1.f, 1.f}, shv = {0.f, 0.f, 0.f, 0.f};
;         if (sc) { scv = *(const f4*)(sc + k) + 1.0f; shv = *(const f4*)(sh + k); }
; #pragma unroll
;         for (int q = 0; q < 4; ++q) {
;             f4 y = v[q][j] * ss[q] * gv;
;             if (sc) y = y * scv + shv;
;             if (OUT_BF16) { v2u w; w.x = cvtpk(y[0], y[1]); w.y = cvtpk(y[2], y[3]); *(v2u*)((bf16*)dst + (size_t)q * dpitch + k) = w; }
;             else { if (NT_OUT) __builtin_nontemporal_store(y, (f4*)((float*)dst + (size_t)q * dpitch + k)); else *(f4*)((float*)dst + (size_t)q * dpitch + k) = y; }
;         }
;     }
	v_fma_f32 v95, -v96, v110, v102
	v_fmac_f32_e32 v99, v98, v106
	s_mov_b64 vcc, s[4:5]
	v_div_fixup_f32 v92, v93, v92, 1.0
	v_div_fmas_f32 v93, v95, v94, v110
	v_fma_f32 v95, -v104, v99, v105
	v_pk_mul_f32 v[52:53], v[52:53], v[90:91] op_sel_hi:[1,0]
	v_pk_mul_f32 v[54:55], v[54:55], v[90:91] op_sel_hi:[1,0]
	s_mov_b64 vcc, s[0:1]
	v_div_fixup_f32 v94, v93, v91, 1.0
	v_div_fmas_f32 v91, v95, v106, v99
	v_pk_mul_f32 v[54:55], v[54:55], v[18:19]
	v_pk_mul_f32 v[52:53], v[52:53], v[16:17]
	v_pk_mul_f32 v[56:57], v[56:57], v[92:93] op_sel_hi:[1,0]
	v_pk_mul_f32 v[58:59], v[58:59], v[92:93] op_sel_hi:[1,0]
	v_div_fixup_f32 v96, v91, v103, 1.0
	global_store_dwordx4 v[74:75], v[52:55], off nt
	v_pk_mul_f32 v[50:51], v[50:51], v[90:91] op_sel_hi:[1,0]
	v_pk_mul_f32 v[48:49], v[48:49], v[90:91] op_sel_hi:[1,0]
	v_pk_mul_f32 v[54:55], v[58:59], v[18:19]
	v_pk_mul_f32 v[52:53], v[56:57], v[16:17]
	v_pk_mul_f32 v[56:57], v[60:61], v[94:95] op_sel_hi:[1,0]
	v_pk_mul_f32 v[58:59], v[62:63], v[94:95] op_sel_hi:[1,0]
	global_store_dwordx4 v[76:77], v[52:55], off nt
	v_pk_mul_f32 v[46:47], v[46:47], v[92:93] op_sel_hi:[1,0]
	v_pk_mul_f32 v[44:45], v[44:45], v[92:93] op_sel_hi:[1,0]
	v_pk_mul_f32 v[54:55], v[18:19], v[58:59]
	v_pk_mul_f32 v[52:53], v[16:17], v[56:57]
	v_pk_mul_f32 v[56:57], v[64:65], v[96:97] op_sel_hi:[1,0]
	v_pk_mul_f32 v[58:59], v[66:67], v[96:97] op_sel_hi:[1,0]
	v_pk_mul_f32 v[16:17], v[16:17], v[56:57]
	v_pk_mul_f32 v[18:19], v[18:19], v[58:59]
	global_store_dwordx4 v[78:79], v[52:55], off nt
	global_store_dwordx4 v[80:81], v[16:19], off nt
	global_load_dwordx4 v[16:19], v[68:69], off offset:1024
	v_pk_mul_f32 v[52:53], v[42:43], v[94:95] op_sel_hi:[1,0]
	v_pk_mul_f32 v[54:55], v[40:41], v[94:95] op_sel_hi:[1,0]
	v_pk_mul_f32 v[56:57], v[38:39], v[96:97] op_sel_hi:[1,0]
	v_pk_mul_f32 v[58:59], v[36:37], v[96:97] op_sel_hi:[1,0]
	v_pk_mul_f32 v[34:35], v[34:35], v[90:91] op_sel_hi:[1,0]
	v_pk_mul_f32 v[32:33], v[32:33], v[90:91] op_sel_hi:[1,0]
	v_pk_mul_f32 v[30:31], v[30:31], v[92:93] op_sel_hi:[1,0]
	v_pk_mul_f32 v[28:29], v[28:29], v[92:93] op_sel_hi:[1,0]
	v_pk_mul_f32 v[2:3], v[2:3], v[90:91] op_sel_hi:[1,0]
	v_pk_mul_f32 v[0:1], v[0:1], v[90:91] op_sel_hi:[1,0]
	v_pk_mul_f32 v[6:7], v[6:7], v[92:93] op_sel_hi:[1,0]
	v_pk_mul_f32 v[4:5], v[4:5], v[92:93] op_sel_hi:[1,0]
	v_pk_mul_f32 v[10:11], v[10:11], v[94:95] op_sel_hi:[1,0]
	v_pk_mul_f32 v[8:9], v[8:9], v[94:95] op_sel_hi:[1,0]
	v_pk_mul_f32 v[14:15], v[14:15], v[96:97] op_sel_hi:[1,0]
	v_pk_mul_f32 v[12:13], v[12:13], v[96:97] op_sel_hi:[1,0]
	s_waitcnt vmcnt(0) lgkmcnt(0)
	v_pk_mul_f32 v[36:37], v[48:49], v[16:17]
	v_pk_mul_f32 v[38:39], v[50:51], v[18:19]
	v_pk_mul_f32 v[40:41], v[44:45], v[16:17]
	v_pk_mul_f32 v[42:43], v[46:47], v[18:19]
	v_pk_mul_f32 v[44:45], v[54:55], v[16:17]
	v_pk_mul_f32 v[46:47], v[52:53], v[18:19]
	v_pk_mul_f32 v[16:17], v[16:17], v[58:59]
	v_pk_mul_f32 v[18:19], v[18:19], v[56:57]
	global_store_dwordx4 v[74:75], v[36:39], off offset:1024 nt
	global_store_dwordx4 v[76:77], v[40:43], off offset:1024 nt
	global_store_dwordx4 v[78:79], v[44:47], off offset:1024 nt
	global_store_dwordx4 v[80:81], v[16:19], off offset:1024 nt
	global_load_dwordx4 v[16:19], v[68:69], off offset:2048
	v_pk_mul_f32 v[36:37], v[26:27], v[94:95] op_sel_hi:[1,0]
	v_pk_mul_f32 v[38:39], v[24:25], v[94:95] op_sel_hi:[1,0]
	v_pk_mul_f32 v[40:41], v[22:23], v[96:97] op_sel_hi:[1,0]
	v_pk_mul_f32 v[42:43], v[20:21], v[96:97] op_sel_hi:[1,0]
	s_waitcnt vmcnt(0) lgkmcnt(0)
	v_pk_mul_f32 v[20:21], v[32:33], v[16:17]
	v_pk_mul_f32 v[22:23], v[34:35], v[18:19]
	v_pk_mul_f32 v[24:25], v[28:29], v[16:17]
	v_pk_mul_f32 v[26:27], v[30:31], v[18:19]
	v_pk_mul_f32 v[28:29], v[38:39], v[16:17]
	v_pk_mul_f32 v[30:31], v[36:37], v[18:19]
	v_pk_mul_f32 v[16:17], v[42:43], v[16:17]
	v_pk_mul_f32 v[18:19], v[40:41], v[18:19]
	global_store_dwordx4 v[74:75], v[20:23], off offset:2048 nt
	global_store_dwordx4 v[76:77], v[24:27], off offset:2048 nt
	global_store_dwordx4 v[78:79], v[28:31], off offset:2048 nt
	global_store_dwordx4 v[80:81], v[16:19], off offset:2048 nt
	global_load_dwordx4 v[16:19], v[68:69], off offset:3072
	s_waitcnt vmcnt(0) lgkmcnt(0)
	v_pk_mul_f32 v[0:1], v[0:1], v[16:17]
	v_pk_mul_f32 v[2:3], v[2:3], v[18:19]
	v_pk_mul_f32 v[4:5], v[4:5], v[16:17]
	v_pk_mul_f32 v[6:7], v[6:7], v[18:19]
	v_pk_mul_f32 v[8:9], v[8:9], v[16:17]
	v_pk_mul_f32 v[10:11], v[10:11], v[18:19]
	v_pk_mul_f32 v[12:13], v[12:13], v[16:17]
	v_pk_mul_f32 v[14:15], v[14:15], v[18:19]
	global_store_dwordx4 v[74:75], v[0:3], off offset:3072 nt
	global_store_dwordx4 v[76:77], v[4:7], off offset:3072 nt
	global_store_dwordx4 v[78:79], v[8:11], off offset:3072 nt
	global_store_dwordx4 v[80:81], v[12:15], off offset:3072 nt
	s_cbranch_scc1 .LBB0_1715
